# GEMM K-loops: one static priority raise for the staggered (trailing) wave half instead of per-segment s_setprio toggling
# speedup vs baseline: 1.0029x; 1.0029x over previous
; #define PG8_BAR __builtin_amdgcn_s_barrier()
;     ...
;     const int wid = __builtin_amdgcn_readfirstlane(tid >> 6), lane = tid & 63, wr = wid >> 2, wc = wid & 3, fr = lane & 15, fq = lane >> 4;
;     const int K = g.K, nt = K / BK;
;     unsigned voffA[2], voffB[2];
; #pragma unroll
;     for (int i = 0; i < 2; ++i) { int R, C; stage_rc(tid * 16 + i * 8192, R, C); const int Rb = Epi::PERM ? ((R & ~31) + perm32(R & 31)) : R;
;         voffA[i] = (unsigned)(R * K + C) * 2u; voffB[i] = (unsigned)(Rb * K + C) * 2u; }
;     const size_t kstep = (size_t)(BK * 2);
;     const size_t hstep = (size_t)HALF * K * 2;
;     const size_t tstep = 2 * hstep;
;     const unsigned ldsw = (unsigned)wid * 1024u;
;     const int aoff = lds_byte(wr * 64 + fr, fq * 8), boff = lds_byte(wc * 32 + fr, fq * 8);
;     ...
;     Unit cur, nxt; int ui = 0;
;     if (!S.next(0, cur)) return;
;     f32x4 acc[2][2][4][2];
; #pragma unroll
;     for (int a = 0; a < 2; ++a)
; #pragma unroll
;         for (int b = 0; b < 2; ++b)
; #pragma unroll
;             for (int m = 0; m < 4; ++m)
; #pragma unroll
;                 for (int n = 0; n < 2; ++n) acc[a][b][m][n] = (f32x4){0.f, 0.f, 0.f, 0.f};
;     bf16x8 At[4][2], B0[2][2], B1[2][2];
;     const char* cA = (const char*)g.A + (size_t)cur.pm * tstep; const char* cB = (const char*)g.Bt + (size_t)cur.pn * tstep;
;     S.a_ready(cur);
;     if constexpr (SP2) {
;         PG8_STAGE(PG8_SB(0, 0), cB, voffB); PG8_STAGE(PG8_SB(0, 1), cB + hstep, voffB); PG8_STAGE(PG8_SA(0, 0), cA, voffA); PG8_STAGE(PG8_SA(0, 1), cA + hstep, voffA);
;         if (wr == 1) PG8_BAR;
.LBB0_187:
	v_readlane_b32 s4, v255, 30
	v_readlane_b32 s5, v255, 31
	s_and_b64 s[4:5], s[4:5], exec
	s_movk_i32 s0, 0x4000
	s_cselect_b32 s0, s0, 0x1000
	v_writelane_b32 v255, s0, 38
	v_readlane_b32 s0, v252, 13
	v_readlane_b32 s4, v253, 32
	v_mbcnt_lo_u32_b32 v0, -1, 0
	v_mbcnt_hi_u32_b32 v0, -1, v0
	v_readlane_b32 s5, v253, 33
	v_add_u32_e32 v1, s0, v0
	s_andn2_b64 vcc, exec, s[4:5]
	v_readfirstlane_b32 s8, v1
	s_cbranch_vccnz .LBB0_219
	v_lshlrev_b32_e32 v4, 4, v1
	v_add_u32_e32 v2, 0x2000, v4
	v_ashrrev_i32_e32 v0, 31, v2
	v_lshrrev_b32_e32 v0, 22, v0
	v_add_u32_e32 v0, v2, v0
	v_ashrrev_i32_e32 v0, 10, v0
	v_mul_i32_i24_e32 v3, 0x400, v0
	v_sub_u32_e32 v2, v2, v3
	v_lshrrev_b32_e32 v3, 4, v2
	v_bitop3_b32 v3, v3, v2, 32 bitop3:0x6c
	v_ashrrev_i32_e32 v2, 31, v3
	v_lshrrev_b32_e32 v2, 26, v2
	v_add_u32_e32 v5, v3, v2
	v_lshlrev_b32_e32 v6, 3, v0
	v_ashrrev_i32_e32 v2, 6, v5
	v_and_b32_e32 v6, -16, v6
	v_add_u32_e32 v6, v2, v6
	v_and_b32_e32 v7, 3, v2
	s_mov_b32 s4, 0x7ffe0
	v_lshrrev_b32_e32 v8, 2, v6
	v_lshlrev_b32_e32 v9, 1, v6
	v_and_b32_e32 v5, 0xc0, v5
	v_and_or_b32 v7, v6, s4, v7
	v_and_b32_e32 v8, 4, v8
	v_and_b32_e32 v9, 24, v9
	v_sub_u32_e32 v3, v3, v5
	v_or3_b32 v7, v7, v8, v9
	v_lshlrev_b32_e32 v8, 5, v0
	v_ashrrev_i16_sdwa v3, v251, sext(v3) dst_sel:DWORD dst_unused:UNUSED_PAD src0_sel:DWORD src1_sel:BYTE_0
	v_and_b32_e32 v8, 32, v8
	v_bfe_i32 v3, v3, 0, 16
	v_add_lshl_u32 v5, v8, v3, 1
	v_lshl_add_u32 v198, v7, 13, v5
	v_lshl_add_u32 v200, v6, 13, v5
	v_bfe_i32 v5, v1, 27, 1
	v_lshrrev_b32_e32 v5, 22, v5
	v_add_u32_e32 v5, v4, v5
	v_and_b32_e32 v5, 0xfffffc00, v5
	v_sub_u32_e32 v4, v4, v5
	v_lshrrev_b32_e32 v5, 4, v4
	v_bitop3_b32 v6, v5, v4, 32 bitop3:0x6c
	v_ashrrev_i32_e32 v5, 31, v1
	v_lshrrev_b32_e32 v5, 26, v5
	v_ashrrev_i32_e32 v4, 31, v6
	v_add_u32_e32 v5, v1, v5
	v_lshrrev_b32_e32 v4, 26, v4
	v_ashrrev_i32_e32 v5, 6, v5
	v_add_u32_e32 v7, v6, v4
	v_lshlrev_b32_e32 v8, 3, v5
	v_ashrrev_i32_e32 v4, 6, v7
	v_and_b32_e32 v8, -16, v8
	v_add_u32_e32 v8, v4, v8
	v_and_b32_e32 v9, 3, v4
	v_lshrrev_b32_e32 v10, 2, v8
	v_lshlrev_b32_e32 v11, 1, v8
	v_and_b32_e32 v7, 0xc0, v7
	v_and_or_b32 v9, v8, s4, v9
	v_and_b32_e32 v10, 4, v10
	v_and_b32_e32 v11, 24, v11
	v_sub_u32_e32 v6, v6, v7
	s_ashr_i32 s9, s8, 6
	v_or3_b32 v9, v9, v10, v11
	v_lshlrev_b32_e32 v10, 5, v5
	v_ashrrev_i16_sdwa v6, v251, sext(v6) dst_sel:DWORD dst_unused:UNUSED_PAD src0_sel:DWORD src1_sel:BYTE_0
	s_lshl_b32 s0, s9, 10
	v_and_b32_e32 v10, 32, v10
	v_bfe_i32 v6, v6, 0, 16
	v_add_lshl_u32 v7, v10, v6, 1
	s_add_i32 s4, s0, 0
	v_readlane_b32 s6, v254, 41
	v_lshl_add_u32 v202, v9, 13, v7
	s_add_i32 m0, s4, 0x10000
	v_readlane_b32 s7, v254, 42
	v_lshl_add_u32 v204, v8, 13, v7
	s_add_i32 s5, s4, 0x2000
	v_readlane_b32 s10, v254, 39
	v_readlane_b32 s11, v254, 40
	s_nop 0
	global_load_lds_dwordx4 v202, s[6:7]
	s_add_i32 m0, s4, 0x12000
	s_nop 0
	global_load_lds_dwordx4 v198, s[6:7]
	v_readlane_b32 s6, v254, 35
	s_add_i32 m0, s4, 0x14000
	v_readlane_b32 s7, v254, 36
	s_nop 4
	global_load_lds_dwordx4 v202, s[6:7]
	s_add_i32 m0, s4, 0x16000
	s_nop 0
	global_load_lds_dwordx4 v198, s[6:7]
	v_readlane_b32 s6, v254, 37
	s_mov_b32 m0, s4
	v_readlane_b32 s7, v254, 38
	s_nop 4
	global_load_lds_dwordx4 v204, s[6:7]
	s_mov_b32 m0, s5
	s_nop 0
	global_load_lds_dwordx4 v200, s[6:7]
	s_add_i32 s6, s4, 0x4000
	s_mov_b32 m0, s6
	s_add_i32 s7, s4, 0x6000
	global_load_lds_dwordx4 v204, s[10:11]
	s_mov_b32 m0, s7
	s_nop 0
	global_load_lds_dwordx4 v200, s[10:11]
	s_ashr_i32 s10, s8, 8
	s_cmp_eq_u32 s10, 1
	s_cselect_b64 s[28:29], -1, 0
	s_cmp_lg_u32 s10, 1
	s_cbranch_scc1 .LBB0_190
	s_barrier
	s_setprio 1

.LBB0_196:
	s_add_u32 s12, s40, 0xfff00080
	s_addc_u32 s13, s41, -1
	s_add_i32 s76, 0, 0x10000
	s_cmp_eq_u32 s75, 60
	s_cselect_b32 s43, s10, s13
	s_cselect_b32 s42, s11, s12
	s_cselect_b32 s25, s63, s74
	s_cselect_b32 s24, s72, s73
	s_add_i32 s12, 0, 0x14000
	v_add_u32_e32 v140, s76, v223
	v_add_u32_e32 v156, s12, v223
	ds_read_b128 v[128:131], v140
	ds_read_b128 v[132:135], v140 offset:1024
	ds_read_b128 v[136:139], v140 offset:2048
	ds_read_b128 v[140:143], v140 offset:3072
	ds_read_b128 v[144:147], v156
	ds_read_b128 v[148:151], v156 offset:1024
	ds_read_b128 v[152:155], v156 offset:2048
	ds_read_b128 v[156:159], v156 offset:3072
	v_lshl_add_u64 v[194:195], s[40:41], 0, v[206:207]
	s_add_i32 m0, s4, 0xc000
	ds_read_b128 v[160:163], v224
	ds_read_b128 v[164:167], v224 offset:1024
	ds_read_b128 v[168:171], v224 offset:2048
	ds_read_b128 v[172:175], v224 offset:3072
	ds_read_b128 v[176:179], v224 offset:4096
	ds_read_b128 v[180:183], v224 offset:5120
	ds_read_b128 v[184:187], v224 offset:6144
	ds_read_b128 v[188:191], v224 offset:7168
	global_load_lds_dwordx4 v[194:195], off
	v_lshl_add_u64 v[194:195], s[40:41], 0, v[208:209]
	s_add_i32 m0, s4, 0xe000
	s_nop 0
	global_load_lds_dwordx4 v[194:195], off
	s_waitcnt vmcnt(8)
	s_waitcnt lgkmcnt(0)
	s_barrier
	s_waitcnt lgkmcnt(0)
	v_mfma_f32_16x16x32_bf16 v[124:127], v[128:131], v[160:163], v[124:127]
	v_mfma_f32_16x16x32_bf16 v[120:123], v[136:139], v[160:163], v[120:123]
	v_mfma_f32_16x16x32_bf16 v[108:111], v[128:131], v[168:171], v[108:111]
	v_mfma_f32_16x16x32_bf16 v[104:107], v[136:139], v[168:171], v[104:107]
	v_mfma_f32_16x16x32_bf16 v[92:95], v[128:131], v[176:179], v[92:95]
	v_mfma_f32_16x16x32_bf16 v[88:91], v[136:139], v[176:179], v[88:91]
	v_mfma_f32_16x16x32_bf16 v[76:79], v[128:131], v[184:187], v[76:79]
	v_mfma_f32_16x16x32_bf16 v[72:75], v[136:139], v[184:187], v[72:75]
	v_mfma_f32_16x16x32_bf16 v[124:127], v[132:135], v[164:167], v[124:127]
	v_mfma_f32_16x16x32_bf16 v[120:123], v[140:143], v[164:167], v[120:123]
	v_mfma_f32_16x16x32_bf16 v[108:111], v[132:135], v[172:175], v[108:111]
	v_mfma_f32_16x16x32_bf16 v[104:107], v[140:143], v[172:175], v[104:107]
	v_mfma_f32_16x16x32_bf16 v[92:95], v[132:135], v[180:183], v[92:95]
	v_mfma_f32_16x16x32_bf16 v[88:91], v[140:143], v[180:183], v[88:91]
	v_mfma_f32_16x16x32_bf16 v[76:79], v[132:135], v[188:191], v[76:79]
	v_mfma_f32_16x16x32_bf16 v[72:75], v[140:143], v[188:191], v[72:75]
	v_mfma_f32_16x16x32_bf16 v[116:119], v[144:147], v[160:163], v[116:119]
	v_mfma_f32_16x16x32_bf16 v[112:115], v[152:155], v[160:163], v[112:115]
	v_mfma_f32_16x16x32_bf16 v[100:103], v[144:147], v[168:171], v[100:103]
	v_mfma_f32_16x16x32_bf16 v[96:99], v[152:155], v[168:171], v[96:99]
	v_mfma_f32_16x16x32_bf16 v[84:87], v[144:147], v[176:179], v[84:87]
	v_mfma_f32_16x16x32_bf16 v[80:83], v[152:155], v[176:179], v[80:83]
	v_mfma_f32_16x16x32_bf16 v[68:71], v[144:147], v[184:187], v[68:71]
	v_mfma_f32_16x16x32_bf16 v[64:67], v[152:155], v[184:187], v[64:67]
	v_mfma_f32_16x16x32_bf16 v[116:119], v[148:151], v[164:167], v[116:119]
	v_mfma_f32_16x16x32_bf16 v[112:115], v[156:159], v[164:167], v[112:115]
	v_mfma_f32_16x16x32_bf16 v[100:103], v[148:151], v[172:175], v[100:103]
	v_mfma_f32_16x16x32_bf16 v[96:99], v[156:159], v[172:175], v[96:99]
	v_mfma_f32_16x16x32_bf16 v[84:87], v[148:151], v[180:183], v[84:87]
	v_mfma_f32_16x16x32_bf16 v[80:83], v[156:159], v[180:183], v[80:83]
	v_mfma_f32_16x16x32_bf16 v[68:71], v[148:151], v[188:191], v[68:71]
	v_mfma_f32_16x16x32_bf16 v[64:67], v[156:159], v[188:191], v[64:67]
	s_barrier
	s_add_i32 s13, s76, s0
	v_lshl_add_u64 v[194:195], s[24:25], 0, v[202:203]
	s_mov_b32 m0, s13
	ds_read_b128 v[160:163], v224 offset:16384
	ds_read_b128 v[164:167], v224 offset:17408
	ds_read_b128 v[168:171], v224 offset:18432
	ds_read_b128 v[172:175], v224 offset:19456
	ds_read_b128 v[176:179], v224 offset:20480
	ds_read_b128 v[180:183], v224 offset:21504
	ds_read_b128 v[184:187], v224 offset:22528
	ds_read_b128 v[188:191], v224 offset:23552
	global_load_lds_dwordx4 v[194:195], off
	s_add_i32 m0, s13, 0x2000
	s_add_u32 s76, s24, 0x100000
	v_lshl_add_u64 v[196:197], s[24:25], 0, v[198:199]
	s_addc_u32 s77, s25, 0
	s_add_i32 s12, s12, s0
	global_load_lds_dwordx4 v[196:197], off
	v_lshl_add_u64 v[210:211], s[76:77], 0, v[202:203]
	s_mov_b32 m0, s12
	v_lshl_add_u64 v[212:213], s[42:43], 0, v[200:201]
	global_load_lds_dwordx4 v[210:211], off
	v_lshl_add_u64 v[210:211], s[76:77], 0, v[198:199]
	s_add_i32 m0, s12, 0x2000
	s_nop 0
	global_load_lds_dwordx4 v[210:211], off
	v_lshl_add_u64 v[210:211], s[42:43], 0, v[204:205]
	s_mov_b32 m0, s4
	s_nop 0
	global_load_lds_dwordx4 v[210:211], off
	s_mov_b32 m0, s5
	s_nop 0
	global_load_lds_dwordx4 v[212:213], off
	s_waitcnt vmcnt(8)
	s_waitcnt lgkmcnt(0)
	s_barrier
	s_waitcnt lgkmcnt(0)
	v_mfma_f32_16x16x32_bf16 v[60:63], v[128:131], v[160:163], v[60:63]
	v_mfma_f32_16x16x32_bf16 v[56:59], v[136:139], v[160:163], v[56:59]
	v_mfma_f32_16x16x32_bf16 v[44:47], v[128:131], v[168:171], v[44:47]
	v_mfma_f32_16x16x32_bf16 v[40:43], v[136:139], v[168:171], v[40:43]
	v_mfma_f32_16x16x32_bf16 v[28:31], v[128:131], v[176:179], v[28:31]
	v_mfma_f32_16x16x32_bf16 v[24:27], v[136:139], v[176:179], v[24:27]
	v_mfma_f32_16x16x32_bf16 v[12:15], v[128:131], v[184:187], v[12:15]
	v_mfma_f32_16x16x32_bf16 v[8:11], v[136:139], v[184:187], v[8:11]
	v_mfma_f32_16x16x32_bf16 v[60:63], v[132:135], v[164:167], v[60:63]
	v_mfma_f32_16x16x32_bf16 v[56:59], v[140:143], v[164:167], v[56:59]
	v_mfma_f32_16x16x32_bf16 v[44:47], v[132:135], v[172:175], v[44:47]
	v_mfma_f32_16x16x32_bf16 v[40:43], v[140:143], v[172:175], v[40:43]
	v_mfma_f32_16x16x32_bf16 v[28:31], v[132:135], v[180:183], v[28:31]
	v_mfma_f32_16x16x32_bf16 v[24:27], v[140:143], v[180:183], v[24:27]
	v_mfma_f32_16x16x32_bf16 v[12:15], v[132:135], v[188:191], v[12:15]
	v_mfma_f32_16x16x32_bf16 v[8:11], v[140:143], v[188:191], v[8:11]
	v_mfma_f32_16x16x32_bf16 v[52:55], v[144:147], v[160:163], v[52:55]
	v_mfma_f32_16x16x32_bf16 v[48:51], v[152:155], v[160:163], v[48:51]
	v_mfma_f32_16x16x32_bf16 v[36:39], v[144:147], v[168:171], v[36:39]
	v_mfma_f32_16x16x32_bf16 v[32:35], v[152:155], v[168:171], v[32:35]
	v_mfma_f32_16x16x32_bf16 v[20:23], v[144:147], v[176:179], v[20:23]
	v_mfma_f32_16x16x32_bf16 v[16:19], v[152:155], v[176:179], v[16:19]
	v_mfma_f32_16x16x32_bf16 v[4:7], v[144:147], v[184:187], v[4:7]
	v_mfma_f32_16x16x32_bf16 v[0:3], v[152:155], v[184:187], v[0:3]
	v_mfma_f32_16x16x32_bf16 v[52:55], v[148:151], v[164:167], v[52:55]
	v_mfma_f32_16x16x32_bf16 v[48:51], v[156:159], v[164:167], v[48:51]
	v_mfma_f32_16x16x32_bf16 v[36:39], v[148:151], v[172:175], v[36:39]
	v_mfma_f32_16x16x32_bf16 v[32:35], v[156:159], v[172:175], v[32:35]
	v_mfma_f32_16x16x32_bf16 v[20:23], v[148:151], v[180:183], v[20:23]
	v_mfma_f32_16x16x32_bf16 v[16:19], v[156:159], v[180:183], v[16:19]
	v_mfma_f32_16x16x32_bf16 v[4:7], v[148:151], v[188:191], v[4:7]
	v_mfma_f32_16x16x32_bf16 v[0:3], v[156:159], v[188:191], v[0:3]
	s_barrier
	s_add_i32 s12, 0, 0x18000
	s_add_i32 s13, 0, 0x1c000
	v_add_u32_e32 v140, s12, v223
	v_add_u32_e32 v156, s13, v223
	ds_read_b128 v[128:131], v140
	ds_read_b128 v[132:135], v140 offset:1024
	ds_read_b128 v[136:139], v140 offset:2048
	ds_read_b128 v[140:143], v140 offset:3072
	ds_read_b128 v[144:147], v156
	ds_read_b128 v[148:151], v156 offset:1024
	ds_read_b128 v[152:155], v156 offset:2048
	ds_read_b128 v[156:159], v156 offset:3072
	s_add_u32 s42, s42, 0x100000
	s_addc_u32 s43, s43, 0
	s_mov_b32 m0, s6
	v_lshl_add_u64 v[214:215], s[42:43], 0, v[204:205]
	ds_read_b128 v[160:163], v224 offset:32768
	ds_read_b128 v[164:167], v224 offset:33792
	ds_read_b128 v[168:171], v224 offset:34816
	ds_read_b128 v[172:175], v224 offset:35840
	ds_read_b128 v[176:179], v224 offset:36864
	ds_read_b128 v[180:183], v224 offset:37888
	ds_read_b128 v[184:187], v224 offset:38912
	ds_read_b128 v[188:191], v224 offset:39936
	global_load_lds_dwordx4 v[214:215], off
	v_lshl_add_u64 v[214:215], s[42:43], 0, v[200:201]
	s_mov_b32 m0, s7
	s_nop 0
	global_load_lds_dwordx4 v[214:215], off
	s_waitcnt vmcnt(8)
	s_waitcnt lgkmcnt(0)
	s_barrier
	s_waitcnt lgkmcnt(0)
	v_mfma_f32_16x16x32_bf16 v[124:127], v[128:131], v[160:163], v[124:127]
	v_mfma_f32_16x16x32_bf16 v[120:123], v[136:139], v[160:163], v[120:123]
	v_mfma_f32_16x16x32_bf16 v[108:111], v[128:131], v[168:171], v[108:111]
	v_mfma_f32_16x16x32_bf16 v[104:107], v[136:139], v[168:171], v[104:107]
	v_mfma_f32_16x16x32_bf16 v[92:95], v[128:131], v[176:179], v[92:95]
	v_mfma_f32_16x16x32_bf16 v[88:91], v[136:139], v[176:179], v[88:91]
	v_mfma_f32_16x16x32_bf16 v[76:79], v[128:131], v[184:187], v[76:79]
	v_mfma_f32_16x16x32_bf16 v[72:75], v[136:139], v[184:187], v[72:75]
	v_mfma_f32_16x16x32_bf16 v[124:127], v[132:135], v[164:167], v[124:127]
	v_mfma_f32_16x16x32_bf16 v[120:123], v[140:143], v[164:167], v[120:123]
	v_mfma_f32_16x16x32_bf16 v[108:111], v[132:135], v[172:175], v[108:111]
	v_mfma_f32_16x16x32_bf16 v[104:107], v[140:143], v[172:175], v[104:107]
	v_mfma_f32_16x16x32_bf16 v[92:95], v[132:135], v[180:183], v[92:95]
	v_mfma_f32_16x16x32_bf16 v[88:91], v[140:143], v[180:183], v[88:91]
	v_mfma_f32_16x16x32_bf16 v[76:79], v[132:135], v[188:191], v[76:79]
	v_mfma_f32_16x16x32_bf16 v[72:75], v[140:143], v[188:191], v[72:75]
	v_mfma_f32_16x16x32_bf16 v[116:119], v[144:147], v[160:163], v[116:119]
	v_mfma_f32_16x16x32_bf16 v[112:115], v[152:155], v[160:163], v[112:115]
	v_mfma_f32_16x16x32_bf16 v[100:103], v[144:147], v[168:171], v[100:103]
	v_mfma_f32_16x16x32_bf16 v[96:99], v[152:155], v[168:171], v[96:99]
	v_mfma_f32_16x16x32_bf16 v[84:87], v[144:147], v[176:179], v[84:87]
	v_mfma_f32_16x16x32_bf16 v[80:83], v[152:155], v[176:179], v[80:83]
	v_mfma_f32_16x16x32_bf16 v[68:71], v[144:147], v[184:187], v[68:71]
	v_mfma_f32_16x16x32_bf16 v[64:67], v[152:155], v[184:187], v[64:67]
	v_mfma_f32_16x16x32_bf16 v[116:119], v[148:151], v[164:167], v[116:119]
	v_mfma_f32_16x16x32_bf16 v[112:115], v[156:159], v[164:167], v[112:115]
	v_mfma_f32_16x16x32_bf16 v[100:103], v[148:151], v[172:175], v[100:103]
	v_mfma_f32_16x16x32_bf16 v[96:99], v[156:159], v[172:175], v[96:99]
	v_mfma_f32_16x16x32_bf16 v[84:87], v[148:151], v[180:183], v[84:87]
	v_mfma_f32_16x16x32_bf16 v[80:83], v[156:159], v[180:183], v[80:83]
	v_mfma_f32_16x16x32_bf16 v[68:71], v[148:151], v[188:191], v[68:71]
	v_mfma_f32_16x16x32_bf16 v[64:67], v[156:159], v[188:191], v[64:67]
	s_barrier
;     ...
;         for (; t < nt; t += 2) {
	s_add_i32 s12, s12, s0
	v_lshl_add_u64 v[194:195], v[194:195], 0, s[34:35]
	s_mov_b32 m0, s12
	ds_read_b128 v[160:163], v224 offset:49152
	ds_read_b128 v[164:167], v224 offset:50176
	ds_read_b128 v[168:171], v224 offset:51200
	ds_read_b128 v[172:175], v224 offset:52224
	ds_read_b128 v[176:179], v224 offset:53248
	ds_read_b128 v[180:183], v224 offset:54272
	ds_read_b128 v[184:187], v224 offset:55296
	ds_read_b128 v[188:191], v224 offset:56320
	global_load_lds_dwordx4 v[194:195], off
	s_add_i32 m0, s12, 0x2000
	s_add_u32 s24, s24, 0x100080
	v_lshl_add_u64 v[194:195], v[196:197], 0, s[34:35]
	s_addc_u32 s25, s25, 0
	s_add_i32 s12, s13, s0
	global_load_lds_dwordx4 v[194:195], off
	v_lshl_add_u64 v[194:195], s[24:25], 0, v[202:203]
	s_mov_b32 m0, s12
	s_nop 0
	global_load_lds_dwordx4 v[194:195], off
	v_lshl_add_u64 v[194:195], s[24:25], 0, v[198:199]
	s_add_i32 m0, s12, 0x2000
	s_nop 0
	global_load_lds_dwordx4 v[194:195], off
	v_lshl_add_u64 v[194:195], v[210:211], 0, s[34:35]
	s_mov_b32 m0, s44
	s_nop 0
	global_load_lds_dwordx4 v[194:195], off
	v_lshl_add_u64 v[194:195], v[212:213], 0, s[34:35]
	s_mov_b32 m0, s45
	s_nop 0
	global_load_lds_dwordx4 v[194:195], off
	s_waitcnt vmcnt(8)
	s_waitcnt lgkmcnt(0)
	s_barrier
	s_waitcnt lgkmcnt(0)
	v_mfma_f32_16x16x32_bf16 v[60:63], v[128:131], v[160:163], v[60:63]
	v_mfma_f32_16x16x32_bf16 v[56:59], v[136:139], v[160:163], v[56:59]
	v_mfma_f32_16x16x32_bf16 v[44:47], v[128:131], v[168:171], v[44:47]
	v_mfma_f32_16x16x32_bf16 v[40:43], v[136:139], v[168:171], v[40:43]
	v_mfma_f32_16x16x32_bf16 v[28:31], v[128:131], v[176:179], v[28:31]
	v_mfma_f32_16x16x32_bf16 v[24:27], v[136:139], v[176:179], v[24:27]
	v_mfma_f32_16x16x32_bf16 v[12:15], v[128:131], v[184:187], v[12:15]
	v_mfma_f32_16x16x32_bf16 v[8:11], v[136:139], v[184:187], v[8:11]
	v_mfma_f32_16x16x32_bf16 v[60:63], v[132:135], v[164:167], v[60:63]
	v_mfma_f32_16x16x32_bf16 v[56:59], v[140:143], v[164:167], v[56:59]
	v_mfma_f32_16x16x32_bf16 v[44:47], v[132:135], v[172:175], v[44:47]
	v_mfma_f32_16x16x32_bf16 v[40:43], v[140:143], v[172:175], v[40:43]
	v_mfma_f32_16x16x32_bf16 v[28:31], v[132:135], v[180:183], v[28:31]
	v_mfma_f32_16x16x32_bf16 v[24:27], v[140:143], v[180:183], v[24:27]
	v_mfma_f32_16x16x32_bf16 v[12:15], v[132:135], v[188:191], v[12:15]
	v_mfma_f32_16x16x32_bf16 v[8:11], v[140:143], v[188:191], v[8:11]
	v_mfma_f32_16x16x32_bf16 v[52:55], v[144:147], v[160:163], v[52:55]
	v_mfma_f32_16x16x32_bf16 v[48:51], v[152:155], v[160:163], v[48:51]
	v_mfma_f32_16x16x32_bf16 v[36:39], v[144:147], v[168:171], v[36:39]
	v_mfma_f32_16x16x32_bf16 v[32:35], v[152:155], v[168:171], v[32:35]
	v_mfma_f32_16x16x32_bf16 v[20:23], v[144:147], v[176:179], v[20:23]
	v_mfma_f32_16x16x32_bf16 v[16:19], v[152:155], v[176:179], v[16:19]
	v_mfma_f32_16x16x32_bf16 v[4:7], v[144:147], v[184:187], v[4:7]
	v_mfma_f32_16x16x32_bf16 v[0:3], v[152:155], v[184:187], v[0:3]
	v_mfma_f32_16x16x32_bf16 v[52:55], v[148:151], v[164:167], v[52:55]
	v_mfma_f32_16x16x32_bf16 v[48:51], v[156:159], v[164:167], v[48:51]
	v_mfma_f32_16x16x32_bf16 v[36:39], v[148:151], v[172:175], v[36:39]
	v_mfma_f32_16x16x32_bf16 v[32:35], v[156:159], v[172:175], v[32:35]
	v_mfma_f32_16x16x32_bf16 v[20:23], v[148:151], v[180:183], v[20:23]
	v_mfma_f32_16x16x32_bf16 v[16:19], v[156:159], v[180:183], v[16:19]
	v_mfma_f32_16x16x32_bf16 v[4:7], v[148:151], v[188:191], v[4:7]
	v_mfma_f32_16x16x32_bf16 v[0:3], v[156:159], v[188:191], v[0:3]
	s_barrier
	s_add_i32 s75, s75, 2
	s_add_u32 s40, s40, 0x100
	s_addc_u32 s41, s41, 0
	s_add_u32 s73, s73, 0x100
	s_addc_u32 s74, s74, 0
	s_cmp_lt_u32 s75, 62
	s_cbranch_scc1 .LBB0_196
	s_andn2_b64 vcc, exec, s[46:47]
	s_cbranch_vccnz .LBB0_199
	s_barrier

; #define PG8_BAR __builtin_amdgcn_s_barrier()
;     ...
;     const int wid = __builtin_amdgcn_readfirstlane(tid >> 6), lane = tid & 63, wr = wid >> 2, wc = wid & 3, fr = lane & 15, fq = lane >> 4;
;     const int K = g.K, nt = K / BK;
;     unsigned voffA[2], voffB[2];
; #pragma unroll
;     for (int i = 0; i < 2; ++i) { int R, C; stage_rc(tid * 16 + i * 8192, R, C); const int Rb = Epi::PERM ? ((R & ~31) + perm32(R & 31)) : R;
;         voffA[i] = (unsigned)(R * K + C) * 2u; voffB[i] = (unsigned)(Rb * K + C) * 2u; }
;     const size_t kstep = (size_t)(BK * 2);
;     const size_t hstep = (size_t)HALF * K * 2;
;     const size_t tstep = 2 * hstep;
;     const unsigned ldsw = (unsigned)wid * 1024u;
;     const int aoff = lds_byte(wr * 64 + fr, fq * 8), boff = lds_byte(wc * 32 + fr, fq * 8);
;     ...
;     Unit cur, nxt; int ui = 0;
;     if (!S.next(0, cur)) return;
;     f32x4 acc[2][2][4][2];
; #pragma unroll
;     for (int a = 0; a < 2; ++a)
; #pragma unroll
;         for (int b = 0; b < 2; ++b)
; #pragma unroll
;             for (int m = 0; m < 4; ++m)
; #pragma unroll
;                 for (int n = 0; n < 2; ++n) acc[a][b][m][n] = (f32x4){0.f, 0.f, 0.f, 0.f};
;     bf16x8 At[4][2], B0[2][2], B1[2][2];
;     const char* cA = (const char*)g.A + (size_t)cur.pm * tstep; const char* cB = (const char*)g.Bt + (size_t)cur.pn * tstep;
;     S.a_ready(cur);
;     if constexpr (SP2) {
;         PG8_STAGE(PG8_SB(0, 0), cB, voffB); PG8_STAGE(PG8_SB(0, 1), cB + hstep, voffB); PG8_STAGE(PG8_SA(0, 0), cA, voffA); PG8_STAGE(PG8_SA(0, 1), cA + hstep, voffA);
;         if (wr == 1) PG8_BAR;
.LBB0_448:
	s_or_b64 exec, exec, s[28:29]
	v_readlane_b32 s4, v255, 39
	s_waitcnt lgkmcnt(0)
	s_barrier
	v_mbcnt_lo_u32_b32 v0, -1, 0
	v_mbcnt_hi_u32_b32 v0, -1, v0
	v_readlane_b32 s5, v255, 40
	v_add_u32_e32 v6, s59, v0
	v_readlane_b32 s90, v255, 19
	v_readlane_b32 s94, v255, 21
	s_and_b64 vcc, exec, s[4:5]
	v_readfirstlane_b32 s24, v6
	v_readlane_b32 s96, v255, 25
	s_movk_i32 s97, 0x181
	v_readlane_b32 s91, v255, 20
	v_readlane_b32 s95, v255, 22
	s_cbranch_vccnz .LBB0_468
	v_lshlrev_b32_e32 v3, 4, v6
	v_add_u32_e32 v1, 0x2000, v3
	v_ashrrev_i32_e32 v0, 31, v1
	v_lshrrev_b32_e32 v0, 22, v0
	v_add_u32_e32 v0, v1, v0
	v_ashrrev_i32_e32 v0, 10, v0
	v_mul_i32_i24_e32 v2, 0x400, v0
	v_sub_u32_e32 v1, v1, v2
	v_lshrrev_b32_e32 v2, 4, v1
	v_bitop3_b32 v2, v2, v1, 32 bitop3:0x6c
	v_ashrrev_i32_e32 v1, 31, v2
	v_lshrrev_b32_e32 v1, 26, v1
	v_add_u32_e32 v4, v2, v1
	v_lshlrev_b32_e32 v5, 3, v0
	v_ashrrev_i32_e32 v1, 6, v4
	v_and_b32_e32 v5, -16, v5
	v_add_u32_e32 v5, v1, v5
	v_and_b32_e32 v7, 3, v1
	s_mov_b32 s4, 0x7ffe0
	v_lshrrev_b32_e32 v8, 2, v5
	v_lshlrev_b32_e32 v9, 1, v5
	v_and_b32_e32 v4, 0xc0, v4
	v_and_or_b32 v7, v5, s4, v7
	v_and_b32_e32 v8, 4, v8
	v_and_b32_e32 v9, 24, v9
	v_sub_u32_e32 v2, v2, v4
	v_or3_b32 v7, v7, v8, v9
	v_lshlrev_b32_e32 v8, 5, v0
	v_ashrrev_i16_sdwa v2, v251, sext(v2) dst_sel:DWORD dst_unused:UNUSED_PAD src0_sel:DWORD src1_sel:BYTE_0
	v_and_b32_e32 v8, 32, v8
	v_bfe_i32 v2, v2, 0, 16
	v_add_lshl_u32 v4, v8, v2, 1
	v_lshl_add_u32 v128, v7, 13, v4
	v_lshl_add_u32 v130, v5, 13, v4
	v_bfe_i32 v4, v6, 27, 1
	v_lshrrev_b32_e32 v4, 22, v4
	v_add_u32_e32 v4, v3, v4
	v_and_b32_e32 v4, 0xfffffc00, v4
	v_sub_u32_e32 v3, v3, v4
	v_lshrrev_b32_e32 v4, 4, v3
	v_bitop3_b32 v5, v4, v3, 32 bitop3:0x6c
	v_ashrrev_i32_e32 v4, 31, v6
	v_lshrrev_b32_e32 v4, 26, v4
	v_ashrrev_i32_e32 v3, 31, v5
	v_add_u32_e32 v4, v6, v4
	v_lshrrev_b32_e32 v3, 26, v3
	v_ashrrev_i32_e32 v4, 6, v4
	v_add_u32_e32 v7, v5, v3
	v_lshlrev_b32_e32 v8, 3, v4
	v_ashrrev_i32_e32 v3, 6, v7
	v_and_b32_e32 v8, -16, v8
	v_add_u32_e32 v8, v3, v8
	v_and_b32_e32 v9, 3, v3
	v_lshrrev_b32_e32 v10, 2, v8
	v_lshlrev_b32_e32 v11, 1, v8
	v_and_b32_e32 v7, 0xc0, v7
	v_and_or_b32 v9, v8, s4, v9
	v_and_b32_e32 v10, 4, v10
	v_and_b32_e32 v11, 24, v11
	v_sub_u32_e32 v5, v5, v7
	s_ashr_i32 s9, s24, 6
	v_or3_b32 v9, v9, v10, v11
	v_lshlrev_b32_e32 v10, 5, v4
	v_ashrrev_i16_sdwa v5, v251, sext(v5) dst_sel:DWORD dst_unused:UNUSED_PAD src0_sel:DWORD src1_sel:BYTE_0
	s_lshl_b32 s0, s9, 10
	v_and_b32_e32 v10, 32, v10
	v_bfe_i32 v5, v5, 0, 16
	v_add_lshl_u32 v7, v10, v5, 1
	s_add_i32 s4, s0, 0
	v_readlane_b32 s6, v253, 61
	v_lshl_add_u32 v192, v9, 13, v7
	s_add_i32 m0, s4, 0x10000
	v_readlane_b32 s7, v253, 62
	v_lshl_add_u32 v132, v8, 13, v7
	s_add_i32 s5, s4, 0x2000
	v_readlane_b32 s10, v253, 59
	v_readlane_b32 s11, v253, 60
	s_nop 0
	global_load_lds_dwordx4 v192, s[6:7]
	s_add_i32 m0, s4, 0x12000
	s_nop 0
	global_load_lds_dwordx4 v128, s[6:7]
	v_readlane_b32 s6, v253, 55
	s_add_i32 m0, s4, 0x14000
	v_readlane_b32 s7, v253, 56
	s_nop 4
	global_load_lds_dwordx4 v192, s[6:7]
	s_add_i32 m0, s4, 0x16000
	s_nop 0
	global_load_lds_dwordx4 v128, s[6:7]
	v_readlane_b32 s6, v253, 57
	s_mov_b32 m0, s4
	v_readlane_b32 s7, v253, 58
	s_nop 4
	global_load_lds_dwordx4 v132, s[6:7]
	s_mov_b32 m0, s5
	s_nop 0
	global_load_lds_dwordx4 v130, s[6:7]
	s_add_i32 s6, s4, 0x4000
	s_mov_b32 m0, s6
	s_add_i32 s7, s4, 0x6000
	global_load_lds_dwordx4 v132, s[10:11]
	s_mov_b32 m0, s7
	s_nop 0
	global_load_lds_dwordx4 v130, s[10:11]
	s_ashr_i32 s10, s24, 8
	s_cmp_eq_u32 s10, 1
	s_cselect_b64 s[28:29], -1, 0
	s_cmp_lg_u32 s10, 1
	s_cbranch_scc1 .LBB0_451
	s_barrier
	s_setprio 1

.LBB0_461:
	s_add_u32 s12, s56, 0xfff00080
	s_addc_u32 s13, s57, -1
	s_add_i32 s74, 0, 0x10000
	s_cmp_eq_u32 s73, 60
	s_cselect_b32 s61, s47, s13
	s_cselect_b32 s60, s59, s12
	v_add_u32_e32 v138, s74, v140
	s_cselect_b32 s25, s43, s72
	s_cselect_b32 s24, s62, s63
	s_add_i32 s12, 0, 0x14000
	ds_read_b128 v[142:145], v138
	ds_read_b128 v[146:149], v138 offset:1024
	ds_read_b128 v[150:153], v138 offset:2048
	ds_read_b128 v[154:157], v138 offset:3072
	v_add_u32_e32 v138, s12, v140
	ds_read_b128 v[158:161], v138
	ds_read_b128 v[162:165], v138 offset:1024
	ds_read_b128 v[166:169], v138 offset:2048
	ds_read_b128 v[170:173], v138 offset:3072
	v_lshl_add_u64 v[138:139], s[56:57], 0, v[134:135]
	s_add_i32 m0, s4, 0xc000
	ds_read_b128 v[174:177], v141
	ds_read_b128 v[178:181], v141 offset:1024
	ds_read_b128 v[182:185], v141 offset:2048
	ds_read_b128 v[186:189], v141 offset:3072
	ds_read_b128 v[194:197], v141 offset:4096
	ds_read_b128 v[198:201], v141 offset:5120
	ds_read_b128 v[202:205], v141 offset:6144
	ds_read_b128 v[206:209], v141 offset:7168
	global_load_lds_dwordx4 v[138:139], off
	v_lshl_add_u64 v[138:139], s[56:57], 0, v[136:137]
	s_add_i32 m0, s4, 0xe000
	s_nop 0
	global_load_lds_dwordx4 v[138:139], off
	s_waitcnt vmcnt(8)
	s_waitcnt lgkmcnt(0)
	s_barrier
	s_waitcnt lgkmcnt(0)
	v_mfma_f32_16x16x32_bf16 v[124:127], v[142:145], v[174:177], v[124:127]
	v_mfma_f32_16x16x32_bf16 v[120:123], v[150:153], v[174:177], v[120:123]
	v_mfma_f32_16x16x32_bf16 v[116:119], v[142:145], v[182:185], v[116:119]
	v_mfma_f32_16x16x32_bf16 v[108:111], v[150:153], v[182:185], v[108:111]
	v_mfma_f32_16x16x32_bf16 v[100:103], v[142:145], v[194:197], v[100:103]
	v_mfma_f32_16x16x32_bf16 v[92:95], v[150:153], v[194:197], v[92:95]
	v_mfma_f32_16x16x32_bf16 v[84:87], v[142:145], v[202:205], v[84:87]
	v_mfma_f32_16x16x32_bf16 v[76:79], v[150:153], v[202:205], v[76:79]
	v_mfma_f32_16x16x32_bf16 v[124:127], v[146:149], v[178:181], v[124:127]
	v_mfma_f32_16x16x32_bf16 v[120:123], v[154:157], v[178:181], v[120:123]
	v_mfma_f32_16x16x32_bf16 v[116:119], v[146:149], v[186:189], v[116:119]
	v_mfma_f32_16x16x32_bf16 v[108:111], v[154:157], v[186:189], v[108:111]
	v_mfma_f32_16x16x32_bf16 v[100:103], v[146:149], v[198:201], v[100:103]
	v_mfma_f32_16x16x32_bf16 v[92:95], v[154:157], v[198:201], v[92:95]
	v_mfma_f32_16x16x32_bf16 v[84:87], v[146:149], v[206:209], v[84:87]
	v_mfma_f32_16x16x32_bf16 v[76:79], v[154:157], v[206:209], v[76:79]
	v_mfma_f32_16x16x32_bf16 v[112:115], v[158:161], v[174:177], v[112:115]
	v_mfma_f32_16x16x32_bf16 v[104:107], v[166:169], v[174:177], v[104:107]
	v_mfma_f32_16x16x32_bf16 v[96:99], v[158:161], v[182:185], v[96:99]
	v_mfma_f32_16x16x32_bf16 v[88:91], v[166:169], v[182:185], v[88:91]
	v_mfma_f32_16x16x32_bf16 v[80:83], v[158:161], v[194:197], v[80:83]
	v_mfma_f32_16x16x32_bf16 v[72:75], v[166:169], v[194:197], v[72:75]
	v_mfma_f32_16x16x32_bf16 v[68:71], v[158:161], v[202:205], v[68:71]
	v_mfma_f32_16x16x32_bf16 v[64:67], v[166:169], v[202:205], v[64:67]
	v_mfma_f32_16x16x32_bf16 v[112:115], v[162:165], v[178:181], v[112:115]
	v_mfma_f32_16x16x32_bf16 v[104:107], v[170:173], v[178:181], v[104:107]
	v_mfma_f32_16x16x32_bf16 v[96:99], v[162:165], v[186:189], v[96:99]
	v_mfma_f32_16x16x32_bf16 v[88:91], v[170:173], v[186:189], v[88:91]
	v_mfma_f32_16x16x32_bf16 v[80:83], v[162:165], v[198:201], v[80:83]
	v_mfma_f32_16x16x32_bf16 v[72:75], v[170:173], v[198:201], v[72:75]
	v_mfma_f32_16x16x32_bf16 v[68:71], v[162:165], v[206:209], v[68:71]
	v_mfma_f32_16x16x32_bf16 v[64:67], v[170:173], v[206:209], v[64:67]
	s_barrier
	s_add_i32 s13, s74, s0
	v_lshl_add_u64 v[138:139], s[24:25], 0, v[192:193]
	s_mov_b32 m0, s13
	ds_read_b128 v[174:177], v141 offset:16384
	ds_read_b128 v[178:181], v141 offset:17408
	ds_read_b128 v[182:185], v141 offset:18432
	ds_read_b128 v[186:189], v141 offset:19456
	ds_read_b128 v[194:197], v141 offset:20480
	ds_read_b128 v[198:201], v141 offset:21504
	ds_read_b128 v[202:205], v141 offset:22528
	ds_read_b128 v[206:209], v141 offset:23552
	global_load_lds_dwordx4 v[138:139], off
	s_add_i32 m0, s13, 0x2000
	s_add_u32 s74, s24, 0x100000
	v_lshl_add_u64 v[190:191], s[24:25], 0, v[128:129]
	s_addc_u32 s75, s25, 0
	s_add_i32 s12, s12, s0
	global_load_lds_dwordx4 v[190:191], off
	v_lshl_add_u64 v[210:211], s[74:75], 0, v[192:193]
	s_mov_b32 m0, s12
	v_lshl_add_u64 v[212:213], s[60:61], 0, v[130:131]
	global_load_lds_dwordx4 v[210:211], off
	v_lshl_add_u64 v[210:211], s[74:75], 0, v[128:129]
	s_add_i32 m0, s12, 0x2000
	s_nop 0
	global_load_lds_dwordx4 v[210:211], off
	v_lshl_add_u64 v[210:211], s[60:61], 0, v[132:133]
	s_mov_b32 m0, s4
	s_nop 0
	global_load_lds_dwordx4 v[210:211], off
	s_mov_b32 m0, s5
	s_nop 0
	global_load_lds_dwordx4 v[212:213], off
	s_waitcnt vmcnt(8)
	s_waitcnt lgkmcnt(0)
	s_barrier
	s_waitcnt lgkmcnt(0)
	v_mfma_f32_16x16x32_bf16 v[60:63], v[142:145], v[174:177], v[60:63]
	v_mfma_f32_16x16x32_bf16 v[56:59], v[150:153], v[174:177], v[56:59]
	v_mfma_f32_16x16x32_bf16 v[52:55], v[142:145], v[182:185], v[52:55]
	v_mfma_f32_16x16x32_bf16 v[44:47], v[150:153], v[182:185], v[44:47]
	v_mfma_f32_16x16x32_bf16 v[36:39], v[142:145], v[194:197], v[36:39]
	v_mfma_f32_16x16x32_bf16 v[28:31], v[150:153], v[194:197], v[28:31]
	v_mfma_f32_16x16x32_bf16 v[20:23], v[142:145], v[202:205], v[20:23]
	v_mfma_f32_16x16x32_bf16 v[12:15], v[150:153], v[202:205], v[12:15]
	v_mfma_f32_16x16x32_bf16 v[60:63], v[146:149], v[178:181], v[60:63]
	v_mfma_f32_16x16x32_bf16 v[56:59], v[154:157], v[178:181], v[56:59]
	v_mfma_f32_16x16x32_bf16 v[52:55], v[146:149], v[186:189], v[52:55]
	v_mfma_f32_16x16x32_bf16 v[44:47], v[154:157], v[186:189], v[44:47]
	v_mfma_f32_16x16x32_bf16 v[36:39], v[146:149], v[198:201], v[36:39]
	v_mfma_f32_16x16x32_bf16 v[28:31], v[154:157], v[198:201], v[28:31]
	v_mfma_f32_16x16x32_bf16 v[20:23], v[146:149], v[206:209], v[20:23]
	v_mfma_f32_16x16x32_bf16 v[12:15], v[154:157], v[206:209], v[12:15]
	v_mfma_f32_16x16x32_bf16 v[48:51], v[158:161], v[174:177], v[48:51]
	v_mfma_f32_16x16x32_bf16 v[40:43], v[166:169], v[174:177], v[40:43]
	v_mfma_f32_16x16x32_bf16 v[32:35], v[158:161], v[182:185], v[32:35]
	v_mfma_f32_16x16x32_bf16 v[24:27], v[166:169], v[182:185], v[24:27]
	v_mfma_f32_16x16x32_bf16 v[16:19], v[158:161], v[194:197], v[16:19]
	v_mfma_f32_16x16x32_bf16 v[8:11], v[166:169], v[194:197], v[8:11]
	v_mfma_f32_16x16x32_bf16 v[4:7], v[158:161], v[202:205], v[4:7]
	v_mfma_f32_16x16x32_bf16 v[0:3], v[166:169], v[202:205], v[0:3]
	v_mfma_f32_16x16x32_bf16 v[48:51], v[162:165], v[178:181], v[48:51]
	v_mfma_f32_16x16x32_bf16 v[40:43], v[170:173], v[178:181], v[40:43]
	v_mfma_f32_16x16x32_bf16 v[32:35], v[162:165], v[186:189], v[32:35]
	v_mfma_f32_16x16x32_bf16 v[24:27], v[170:173], v[186:189], v[24:27]
	v_mfma_f32_16x16x32_bf16 v[16:19], v[162:165], v[198:201], v[16:19]
	v_mfma_f32_16x16x32_bf16 v[8:11], v[170:173], v[198:201], v[8:11]
	v_mfma_f32_16x16x32_bf16 v[4:7], v[162:165], v[206:209], v[4:7]
	v_mfma_f32_16x16x32_bf16 v[0:3], v[170:173], v[206:209], v[0:3]
	s_barrier
	s_add_i32 s12, 0, 0x18000
	s_add_i32 s13, 0, 0x1c000
	v_add_u32_e32 v154, s12, v140
	v_add_u32_e32 v170, s13, v140
	ds_read_b128 v[142:145], v154
	ds_read_b128 v[146:149], v154 offset:1024
	ds_read_b128 v[150:153], v154 offset:2048
	ds_read_b128 v[154:157], v154 offset:3072
	ds_read_b128 v[158:161], v170
	ds_read_b128 v[162:165], v170 offset:1024
	ds_read_b128 v[166:169], v170 offset:2048
	ds_read_b128 v[170:173], v170 offset:3072
	s_add_u32 s60, s60, 0x100000
	s_addc_u32 s61, s61, 0
	s_mov_b32 m0, s6
	v_lshl_add_u64 v[214:215], s[60:61], 0, v[132:133]
	ds_read_b128 v[174:177], v141 offset:32768
	ds_read_b128 v[178:181], v141 offset:33792
	ds_read_b128 v[182:185], v141 offset:34816
	ds_read_b128 v[186:189], v141 offset:35840
	ds_read_b128 v[194:197], v141 offset:36864
	ds_read_b128 v[198:201], v141 offset:37888
	ds_read_b128 v[202:205], v141 offset:38912
	ds_read_b128 v[206:209], v141 offset:39936
	global_load_lds_dwordx4 v[214:215], off
	v_lshl_add_u64 v[214:215], s[60:61], 0, v[130:131]
	s_mov_b32 m0, s7
	s_nop 0
	global_load_lds_dwordx4 v[214:215], off
	s_waitcnt vmcnt(8)
	s_waitcnt lgkmcnt(0)
	s_barrier
	s_waitcnt lgkmcnt(0)
	v_mfma_f32_16x16x32_bf16 v[124:127], v[142:145], v[174:177], v[124:127]
	v_mfma_f32_16x16x32_bf16 v[120:123], v[150:153], v[174:177], v[120:123]
	v_mfma_f32_16x16x32_bf16 v[116:119], v[142:145], v[182:185], v[116:119]
	v_mfma_f32_16x16x32_bf16 v[108:111], v[150:153], v[182:185], v[108:111]
	v_mfma_f32_16x16x32_bf16 v[100:103], v[142:145], v[194:197], v[100:103]
	v_mfma_f32_16x16x32_bf16 v[92:95], v[150:153], v[194:197], v[92:95]
	v_mfma_f32_16x16x32_bf16 v[84:87], v[142:145], v[202:205], v[84:87]
	v_mfma_f32_16x16x32_bf16 v[76:79], v[150:153], v[202:205], v[76:79]
	v_mfma_f32_16x16x32_bf16 v[124:127], v[146:149], v[178:181], v[124:127]
	v_mfma_f32_16x16x32_bf16 v[120:123], v[154:157], v[178:181], v[120:123]
	v_mfma_f32_16x16x32_bf16 v[116:119], v[146:149], v[186:189], v[116:119]
	v_mfma_f32_16x16x32_bf16 v[108:111], v[154:157], v[186:189], v[108:111]
	v_mfma_f32_16x16x32_bf16 v[100:103], v[146:149], v[198:201], v[100:103]
	v_mfma_f32_16x16x32_bf16 v[92:95], v[154:157], v[198:201], v[92:95]
	v_mfma_f32_16x16x32_bf16 v[84:87], v[146:149], v[206:209], v[84:87]
	v_mfma_f32_16x16x32_bf16 v[76:79], v[154:157], v[206:209], v[76:79]
	v_mfma_f32_16x16x32_bf16 v[112:115], v[158:161], v[174:177], v[112:115]
	v_mfma_f32_16x16x32_bf16 v[104:107], v[166:169], v[174:177], v[104:107]
	v_mfma_f32_16x16x32_bf16 v[96:99], v[158:161], v[182:185], v[96:99]
	v_mfma_f32_16x16x32_bf16 v[88:91], v[166:169], v[182:185], v[88:91]
	v_mfma_f32_16x16x32_bf16 v[80:83], v[158:161], v[194:197], v[80:83]
	v_mfma_f32_16x16x32_bf16 v[72:75], v[166:169], v[194:197], v[72:75]
	v_mfma_f32_16x16x32_bf16 v[68:71], v[158:161], v[202:205], v[68:71]
	v_mfma_f32_16x16x32_bf16 v[64:67], v[166:169], v[202:205], v[64:67]
	v_mfma_f32_16x16x32_bf16 v[112:115], v[162:165], v[178:181], v[112:115]
	v_mfma_f32_16x16x32_bf16 v[104:107], v[170:173], v[178:181], v[104:107]
	v_mfma_f32_16x16x32_bf16 v[96:99], v[162:165], v[186:189], v[96:99]
	v_mfma_f32_16x16x32_bf16 v[88:91], v[170:173], v[186:189], v[88:91]
	v_mfma_f32_16x16x32_bf16 v[80:83], v[162:165], v[198:201], v[80:83]
	v_mfma_f32_16x16x32_bf16 v[72:75], v[170:173], v[198:201], v[72:75]
	v_mfma_f32_16x16x32_bf16 v[68:71], v[162:165], v[206:209], v[68:71]
	v_mfma_f32_16x16x32_bf16 v[64:67], v[170:173], v[206:209], v[64:67]
	s_barrier
;     ...
;         for (; t < nt; t += 2) {
	s_add_i32 s12, s12, s0
	v_lshl_add_u64 v[138:139], v[138:139], 0, s[34:35]
	s_mov_b32 m0, s12
	ds_read_b128 v[174:177], v141 offset:49152
	ds_read_b128 v[178:181], v141 offset:50176
	ds_read_b128 v[182:185], v141 offset:51200
	ds_read_b128 v[186:189], v141 offset:52224
	ds_read_b128 v[194:197], v141 offset:53248
	ds_read_b128 v[198:201], v141 offset:54272
	ds_read_b128 v[202:205], v141 offset:55296
	ds_read_b128 v[206:209], v141 offset:56320
	global_load_lds_dwordx4 v[138:139], off
	s_add_i32 m0, s12, 0x2000
	s_add_u32 s24, s24, 0x100080
	v_lshl_add_u64 v[138:139], v[190:191], 0, s[34:35]
	s_addc_u32 s25, s25, 0
	s_add_i32 s12, s13, s0
	global_load_lds_dwordx4 v[138:139], off
	v_lshl_add_u64 v[138:139], s[24:25], 0, v[192:193]
	s_mov_b32 m0, s12
	s_nop 0
	global_load_lds_dwordx4 v[138:139], off
	v_lshl_add_u64 v[138:139], s[24:25], 0, v[128:129]
	s_add_i32 m0, s12, 0x2000
	s_nop 0
	global_load_lds_dwordx4 v[138:139], off
	v_lshl_add_u64 v[138:139], v[210:211], 0, s[34:35]
	s_mov_b32 m0, s10
	s_nop 0
	global_load_lds_dwordx4 v[138:139], off
	v_lshl_add_u64 v[138:139], v[212:213], 0, s[34:35]
	s_mov_b32 m0, s11
	s_nop 0
	global_load_lds_dwordx4 v[138:139], off
	s_waitcnt vmcnt(8)
	s_waitcnt lgkmcnt(0)
	s_barrier
	s_waitcnt lgkmcnt(0)
	v_mfma_f32_16x16x32_bf16 v[60:63], v[142:145], v[174:177], v[60:63]
	v_mfma_f32_16x16x32_bf16 v[56:59], v[150:153], v[174:177], v[56:59]
	v_mfma_f32_16x16x32_bf16 v[52:55], v[142:145], v[182:185], v[52:55]
	v_mfma_f32_16x16x32_bf16 v[44:47], v[150:153], v[182:185], v[44:47]
	v_mfma_f32_16x16x32_bf16 v[36:39], v[142:145], v[194:197], v[36:39]
	v_mfma_f32_16x16x32_bf16 v[28:31], v[150:153], v[194:197], v[28:31]
	v_mfma_f32_16x16x32_bf16 v[20:23], v[142:145], v[202:205], v[20:23]
	v_mfma_f32_16x16x32_bf16 v[12:15], v[150:153], v[202:205], v[12:15]
	v_mfma_f32_16x16x32_bf16 v[60:63], v[146:149], v[178:181], v[60:63]
	v_mfma_f32_16x16x32_bf16 v[56:59], v[154:157], v[178:181], v[56:59]
	v_mfma_f32_16x16x32_bf16 v[52:55], v[146:149], v[186:189], v[52:55]
	v_mfma_f32_16x16x32_bf16 v[44:47], v[154:157], v[186:189], v[44:47]
	v_mfma_f32_16x16x32_bf16 v[36:39], v[146:149], v[198:201], v[36:39]
	v_mfma_f32_16x16x32_bf16 v[28:31], v[154:157], v[198:201], v[28:31]
	v_mfma_f32_16x16x32_bf16 v[20:23], v[146:149], v[206:209], v[20:23]
	v_mfma_f32_16x16x32_bf16 v[12:15], v[154:157], v[206:209], v[12:15]
	v_mfma_f32_16x16x32_bf16 v[48:51], v[158:161], v[174:177], v[48:51]
	v_mfma_f32_16x16x32_bf16 v[40:43], v[166:169], v[174:177], v[40:43]
	v_mfma_f32_16x16x32_bf16 v[32:35], v[158:161], v[182:185], v[32:35]
	v_mfma_f32_16x16x32_bf16 v[24:27], v[166:169], v[182:185], v[24:27]
	v_mfma_f32_16x16x32_bf16 v[16:19], v[158:161], v[194:197], v[16:19]
	v_mfma_f32_16x16x32_bf16 v[8:11], v[166:169], v[194:197], v[8:11]
	v_mfma_f32_16x16x32_bf16 v[4:7], v[158:161], v[202:205], v[4:7]
	v_mfma_f32_16x16x32_bf16 v[0:3], v[166:169], v[202:205], v[0:3]
	v_mfma_f32_16x16x32_bf16 v[48:51], v[162:165], v[178:181], v[48:51]
	v_mfma_f32_16x16x32_bf16 v[40:43], v[170:173], v[178:181], v[40:43]
	v_mfma_f32_16x16x32_bf16 v[32:35], v[162:165], v[186:189], v[32:35]
	v_mfma_f32_16x16x32_bf16 v[24:27], v[170:173], v[186:189], v[24:27]
	v_mfma_f32_16x16x32_bf16 v[16:19], v[162:165], v[198:201], v[16:19]
	v_mfma_f32_16x16x32_bf16 v[8:11], v[170:173], v[198:201], v[8:11]
	v_mfma_f32_16x16x32_bf16 v[4:7], v[162:165], v[206:209], v[4:7]
	v_mfma_f32_16x16x32_bf16 v[0:3], v[170:173], v[206:209], v[0:3]
	s_barrier
	s_add_i32 s73, s73, 2
	s_add_u32 s56, s56, 0x100
	s_addc_u32 s57, s57, 0
	s_add_u32 s63, s63, 0x100
	s_addc_u32 s72, s72, 0
	s_cmp_lt_u32 s73, 62
	s_cbranch_scc1 .LBB0_461
	s_andn2_b64 vcc, exec, s[38:39]
	s_cbranch_vccnz .LBB0_464
	s_barrier

; #define PG8_BAR __builtin_amdgcn_s_barrier()
;     ...
;     const int wid = __builtin_amdgcn_readfirstlane(tid >> 6), lane = tid & 63, wr = wid >> 2, wc = wid & 3, fr = lane & 15, fq = lane >> 4;
;     const int K = g.K, nt = K / BK;
;     unsigned voffA[2], voffB[2];
; #pragma unroll
;     for (int i = 0; i < 2; ++i) { int R, C; stage_rc(tid * 16 + i * 8192, R, C); const int Rb = Epi::PERM ? ((R & ~31) + perm32(R & 31)) : R;
;         voffA[i] = (unsigned)(R * K + C) * 2u; voffB[i] = (unsigned)(Rb * K + C) * 2u; }
;     const size_t kstep = (size_t)(BK * 2);
;     const size_t hstep = (size_t)HALF * K * 2;
;     const size_t tstep = 2 * hstep;
;     const unsigned ldsw = (unsigned)wid * 1024u;
;     const int aoff = lds_byte(wr * 64 + fr, fq * 8), boff = lds_byte(wc * 32 + fr, fq * 8);
;     ...
;     Unit cur, nxt; int ui = 0;
;     if (!S.next(0, cur)) return;
;     f32x4 acc[2][2][4][2];
; #pragma unroll
;     for (int a = 0; a < 2; ++a)
; #pragma unroll
;         for (int b = 0; b < 2; ++b)
; #pragma unroll
;             for (int m = 0; m < 4; ++m)
; #pragma unroll
;                 for (int n = 0; n < 2; ++n) acc[a][b][m][n] = (f32x4){0.f, 0.f, 0.f, 0.f};
;     bf16x8 At[4][2], B0[2][2], B1[2][2];
;     const char* cA = (const char*)g.A + (size_t)cur.pm * tstep; const char* cB = (const char*)g.Bt + (size_t)cur.pn * tstep;
;     S.a_ready(cur);
;     if constexpr (SP2) {
;         PG8_STAGE(PG8_SB(0, 0), cB, voffB); PG8_STAGE(PG8_SB(0, 1), cB + hstep, voffB); PG8_STAGE(PG8_SA(0, 0), cA, voffA); PG8_STAGE(PG8_SA(0, 1), cA + hstep, voffA);
;         if (wr == 1) PG8_BAR;
.LBB0_543:
	s_or_b64 exec, exec, s[28:29]
	v_readlane_b32 s4, v253, 50
	s_waitcnt lgkmcnt(0)
	s_barrier
	v_mbcnt_lo_u32_b32 v0, -1, 0
	v_mbcnt_hi_u32_b32 v0, -1, v0
	v_readlane_b32 s5, v253, 51
	v_add_u32_e32 v6, s59, v0
	s_andn2_b64 vcc, exec, s[4:5]
	v_readfirstlane_b32 s4, v6
	s_cbranch_vccnz .LBB0_563
	v_lshlrev_b32_e32 v3, 4, v6
	v_add_u32_e32 v1, 0x2000, v3
	v_ashrrev_i32_e32 v0, 31, v1
	v_lshrrev_b32_e32 v0, 22, v0
	v_add_u32_e32 v0, v1, v0
	v_ashrrev_i32_e32 v0, 10, v0
	v_mul_i32_i24_e32 v2, 0x400, v0
	v_sub_u32_e32 v1, v1, v2
	v_lshrrev_b32_e32 v2, 4, v1
	v_bitop3_b32 v2, v2, v1, 32 bitop3:0x6c
	v_ashrrev_i32_e32 v1, 31, v2
	v_lshrrev_b32_e32 v1, 26, v1
	v_add_u32_e32 v4, v2, v1
	v_lshlrev_b32_e32 v5, 3, v0
	v_ashrrev_i32_e32 v1, 6, v4
	v_and_b32_e32 v5, -16, v5
	v_add_u32_e32 v5, v1, v5
	v_and_b32_e32 v7, 3, v1
	s_mov_b32 s6, 0xfffe0
	v_lshrrev_b32_e32 v8, 2, v5
	v_lshlrev_b32_e32 v9, 1, v5
	v_and_b32_e32 v4, 0xc0, v4
	v_and_or_b32 v7, v5, s6, v7
	v_and_b32_e32 v8, 4, v8
	v_and_b32_e32 v9, 24, v9
	v_sub_u32_e32 v2, v2, v4
	v_or3_b32 v7, v7, v8, v9
	v_lshlrev_b32_e32 v8, 5, v0
	v_ashrrev_i16_sdwa v2, v251, sext(v2) dst_sel:DWORD dst_unused:UNUSED_PAD src0_sel:DWORD src1_sel:BYTE_0
	v_and_b32_e32 v8, 32, v8
	v_bfe_i32 v2, v2, 0, 16
	v_add_lshl_u32 v4, v8, v2, 1
	v_lshl_add_u32 v144, v7, 12, v4
	v_lshl_add_u32 v146, v5, 12, v4
	v_bfe_i32 v4, v6, 27, 1
	v_lshrrev_b32_e32 v4, 22, v4
	v_add_u32_e32 v4, v3, v4
	v_and_b32_e32 v4, 0xfffffc00, v4
	v_sub_u32_e32 v3, v3, v4
	v_lshrrev_b32_e32 v4, 4, v3
	v_bitop3_b32 v5, v4, v3, 32 bitop3:0x6c
	v_ashrrev_i32_e32 v4, 31, v6
	v_lshrrev_b32_e32 v4, 26, v4
	v_ashrrev_i32_e32 v3, 31, v5
	v_add_u32_e32 v4, v6, v4
	v_lshrrev_b32_e32 v3, 26, v3
	v_ashrrev_i32_e32 v4, 6, v4
	v_add_u32_e32 v7, v5, v3
	v_lshlrev_b32_e32 v8, 3, v4
	v_ashrrev_i32_e32 v3, 6, v7
	v_and_b32_e32 v8, -16, v8
	v_add_u32_e32 v8, v3, v8
	v_and_b32_e32 v9, 3, v3
	v_lshrrev_b32_e32 v10, 2, v8
	v_lshlrev_b32_e32 v11, 1, v8
	v_and_b32_e32 v7, 0xc0, v7
	v_and_or_b32 v9, v8, s6, v9
	v_and_b32_e32 v10, 4, v10
	v_and_b32_e32 v11, 24, v11
	v_sub_u32_e32 v5, v5, v7
	s_ashr_i32 s5, s4, 6
	v_or3_b32 v9, v9, v10, v11
	v_lshlrev_b32_e32 v10, 5, v4
	v_ashrrev_i16_sdwa v5, v251, sext(v5) dst_sel:DWORD dst_unused:UNUSED_PAD src0_sel:DWORD src1_sel:BYTE_0
	s_lshl_b32 s0, s5, 10
	v_and_b32_e32 v10, 32, v10
	v_bfe_i32 v5, v5, 0, 16
	v_add_lshl_u32 v7, v10, v5, 1
	s_add_i32 s56, s0, 0
	v_readlane_b32 s6, v254, 12
	v_lshl_add_u32 v192, v9, 12, v7
	s_add_i32 m0, s56, 0x10000
	v_readlane_b32 s7, v254, 13
	v_lshl_add_u32 v148, v8, 12, v7
	s_add_i32 s57, s56, 0x2000
	s_add_i32 s62, s56, 0x4000
	s_add_i32 s63, s56, 0x6000
	s_nop 0
	global_load_lds_dwordx4 v192, s[6:7]
	s_add_i32 m0, s56, 0x12000
	s_nop 0
	global_load_lds_dwordx4 v144, s[6:7]
	v_readlane_b32 s6, v254, 4
	s_add_i32 m0, s56, 0x14000
	v_readlane_b32 s7, v254, 5
	s_nop 4
	global_load_lds_dwordx4 v192, s[6:7]
	s_add_i32 m0, s56, 0x16000
	s_nop 0
	global_load_lds_dwordx4 v144, s[6:7]
	v_readlane_b32 s6, v254, 8
	s_mov_b32 m0, s56
	v_readlane_b32 s7, v254, 9
	s_nop 4
	global_load_lds_dwordx4 v148, s[6:7]
	s_mov_b32 m0, s57
	s_nop 0
	global_load_lds_dwordx4 v146, s[6:7]
	v_readlane_b32 s6, v254, 10
	s_mov_b32 m0, s62
	v_readlane_b32 s7, v254, 11
	s_nop 4
	global_load_lds_dwordx4 v148, s[6:7]
	s_mov_b32 m0, s63
	s_nop 0
	global_load_lds_dwordx4 v146, s[6:7]
	s_ashr_i32 s6, s4, 8
	s_cmp_eq_u32 s6, 1
	s_cselect_b64 s[42:43], -1, 0
	s_cmp_lg_u32 s6, 1
	s_cbranch_scc1 .LBB0_546
	s_barrier
	s_setprio 1

.LBB0_552:
	s_add_u32 s12, s50, 0xfff80080
	s_addc_u32 s13, s51, -1
	s_add_i32 s44, 0, 0x10000
	s_cmp_eq_u32 s29, 28
	s_cselect_b32 s53, s6, s13
	s_cselect_b32 s52, s7, s12
	s_cselect_b32 s25, s8, s11
	s_cselect_b32 s24, s9, s10
	s_add_i32 s12, 0, 0x14000
	s_waitcnt vmcnt(0)
	v_add_u32_e32 v60, s44, v198
	v_add_u32_e32 v166, s12, v198
	ds_read_b128 v[20:23], v60
	ds_read_b128 v[32:35], v60 offset:1024
	ds_read_b128 v[56:59], v60 offset:2048
	ds_read_b128 v[60:63], v60 offset:3072
	ds_read_b128 v[154:157], v166
	ds_read_b128 v[158:161], v166 offset:1024
	ds_read_b128 v[162:165], v166 offset:2048
	ds_read_b128 v[166:169], v166 offset:3072
	v_lshl_add_u64 v[190:191], s[50:51], 0, v[150:151]
	s_add_i32 m0, s56, 0xc000
	ds_read_b128 v[170:173], v199
	ds_read_b128 v[174:177], v199 offset:1024
	ds_read_b128 v[178:181], v199 offset:2048
	ds_read_b128 v[182:185], v199 offset:3072
	ds_read_b128 v[186:189], v199 offset:4096
	ds_read_b128 v[194:197], v199 offset:5120
	ds_read_b128 v[200:203], v199 offset:6144
	ds_read_b128 v[204:207], v199 offset:7168
	global_load_lds_dwordx4 v[190:191], off
	v_lshl_add_u64 v[190:191], s[50:51], 0, v[152:153]
	s_add_i32 m0, s56, 0xe000
	s_nop 0
	global_load_lds_dwordx4 v[190:191], off
	s_waitcnt vmcnt(8)
	s_waitcnt lgkmcnt(0)
	s_barrier
	s_waitcnt lgkmcnt(0)
	v_mfma_i32_16x16x64_i8 v[140:143], v[20:23], v[170:173], v[140:143]
	v_mfma_i32_16x16x64_i8 v[136:139], v[56:59], v[170:173], v[136:139]
	v_mfma_i32_16x16x64_i8 v[132:135], v[20:23], v[178:181], v[132:135]
	v_mfma_i32_16x16x64_i8 v[124:127], v[56:59], v[178:181], v[124:127]
	v_mfma_i32_16x16x64_i8 v[116:119], v[20:23], v[186:189], v[116:119]
	v_mfma_i32_16x16x64_i8 v[108:111], v[56:59], v[186:189], v[108:111]
	v_mfma_i32_16x16x64_i8 v[100:103], v[20:23], v[200:203], v[100:103]
	v_mfma_i32_16x16x64_i8 v[92:95], v[56:59], v[200:203], v[92:95]
	v_mfma_i32_16x16x64_i8 v[140:143], v[32:35], v[174:177], v[140:143]
	v_mfma_i32_16x16x64_i8 v[136:139], v[60:63], v[174:177], v[136:139]
	v_mfma_i32_16x16x64_i8 v[132:135], v[32:35], v[182:185], v[132:135]
	v_mfma_i32_16x16x64_i8 v[124:127], v[60:63], v[182:185], v[124:127]
	v_mfma_i32_16x16x64_i8 v[116:119], v[32:35], v[194:197], v[116:119]
	v_mfma_i32_16x16x64_i8 v[108:111], v[60:63], v[194:197], v[108:111]
	v_mfma_i32_16x16x64_i8 v[100:103], v[32:35], v[204:207], v[100:103]
	v_mfma_i32_16x16x64_i8 v[92:95], v[60:63], v[204:207], v[92:95]
	v_mfma_i32_16x16x64_i8 v[128:131], v[154:157], v[170:173], v[128:131]
	v_mfma_i32_16x16x64_i8 v[120:123], v[162:165], v[170:173], v[120:123]
	v_mfma_i32_16x16x64_i8 v[112:115], v[154:157], v[178:181], v[112:115]
	v_mfma_i32_16x16x64_i8 v[104:107], v[162:165], v[178:181], v[104:107]
	v_mfma_i32_16x16x64_i8 v[96:99], v[154:157], v[186:189], v[96:99]
	v_mfma_i32_16x16x64_i8 v[88:91], v[162:165], v[186:189], v[88:91]
	v_mfma_i32_16x16x64_i8 v[84:87], v[154:157], v[200:203], v[84:87]
	v_mfma_i32_16x16x64_i8 v[80:83], v[162:165], v[200:203], v[80:83]
	v_mfma_i32_16x16x64_i8 v[128:131], v[158:161], v[174:177], v[128:131]
	v_mfma_i32_16x16x64_i8 v[120:123], v[166:169], v[174:177], v[120:123]
	v_mfma_i32_16x16x64_i8 v[112:115], v[158:161], v[182:185], v[112:115]
	v_mfma_i32_16x16x64_i8 v[104:107], v[166:169], v[182:185], v[104:107]
	v_mfma_i32_16x16x64_i8 v[96:99], v[158:161], v[194:197], v[96:99]
	v_mfma_i32_16x16x64_i8 v[88:91], v[166:169], v[194:197], v[88:91]
	v_mfma_i32_16x16x64_i8 v[84:87], v[158:161], v[204:207], v[84:87]
	v_mfma_i32_16x16x64_i8 v[80:83], v[166:169], v[204:207], v[80:83]
	s_barrier
	s_add_i32 s13, s44, s0
	v_lshl_add_u64 v[190:191], s[24:25], 0, v[192:193]
	s_mov_b32 m0, s13
	ds_read_b128 v[170:173], v199 offset:16384
	ds_read_b128 v[174:177], v199 offset:17408
	ds_read_b128 v[178:181], v199 offset:18432
	ds_read_b128 v[182:185], v199 offset:19456
	ds_read_b128 v[186:189], v199 offset:20480
	ds_read_b128 v[194:197], v199 offset:21504
	ds_read_b128 v[200:203], v199 offset:22528
	ds_read_b128 v[204:207], v199 offset:23552
	global_load_lds_dwordx4 v[190:191], off
	s_add_i32 m0, s13, 0x2000
	s_add_u32 s44, s24, 0x80000
	v_lshl_add_u64 v[208:209], s[24:25], 0, v[144:145]
	s_addc_u32 s45, s25, 0
	s_add_i32 s12, s12, s0
	global_load_lds_dwordx4 v[208:209], off
	v_lshl_add_u64 v[210:211], s[44:45], 0, v[192:193]
	s_mov_b32 m0, s12
	v_lshl_add_u64 v[212:213], s[52:53], 0, v[146:147]
	global_load_lds_dwordx4 v[210:211], off
	v_lshl_add_u64 v[210:211], s[44:45], 0, v[144:145]
	s_add_i32 m0, s12, 0x2000
	s_nop 0
	global_load_lds_dwordx4 v[210:211], off
	v_lshl_add_u64 v[210:211], s[52:53], 0, v[148:149]
	s_mov_b32 m0, s56
	s_nop 0
	global_load_lds_dwordx4 v[210:211], off
	s_mov_b32 m0, s57
	s_nop 0
	global_load_lds_dwordx4 v[212:213], off
	s_waitcnt vmcnt(8)
	s_waitcnt lgkmcnt(0)
	s_barrier
	s_waitcnt lgkmcnt(0)
	v_mfma_i32_16x16x64_i8 v[76:79], v[20:23], v[170:173], v[76:79]
	v_mfma_i32_16x16x64_i8 v[72:75], v[56:59], v[170:173], v[72:75]
	v_mfma_i32_16x16x64_i8 v[52:55], v[20:23], v[178:181], v[52:55]
	v_mfma_i32_16x16x64_i8 v[44:47], v[56:59], v[178:181], v[44:47]
	v_mfma_i32_16x16x64_i8 v[36:39], v[20:23], v[186:189], v[36:39]
	v_mfma_i32_16x16x64_i8 v[24:27], v[56:59], v[186:189], v[24:27]
	v_mfma_i32_16x16x64_i8 v[12:15], v[20:23], v[200:203], v[12:15]
	v_mfma_i32_16x16x64_i8 v[4:7], v[56:59], v[200:203], v[4:7]
	v_mfma_i32_16x16x64_i8 v[76:79], v[32:35], v[174:177], v[76:79]
	v_mfma_i32_16x16x64_i8 v[72:75], v[60:63], v[174:177], v[72:75]
	v_mfma_i32_16x16x64_i8 v[52:55], v[32:35], v[182:185], v[52:55]
	v_mfma_i32_16x16x64_i8 v[44:47], v[60:63], v[182:185], v[44:47]
	v_mfma_i32_16x16x64_i8 v[36:39], v[32:35], v[194:197], v[36:39]
	v_mfma_i32_16x16x64_i8 v[24:27], v[60:63], v[194:197], v[24:27]
	v_mfma_i32_16x16x64_i8 v[12:15], v[32:35], v[204:207], v[12:15]
	v_mfma_i32_16x16x64_i8 v[4:7], v[60:63], v[204:207], v[4:7]
	v_mfma_i32_16x16x64_i8 v[48:51], v[154:157], v[178:181], v[48:51]
	v_mfma_i32_16x16x64_i8 v[40:43], v[162:165], v[178:181], v[40:43]
	v_mfma_i32_16x16x64_i8 v[28:31], v[154:157], v[186:189], v[28:31]
	v_mfma_i32_16x16x64_i8 v[16:19], v[162:165], v[186:189], v[16:19]
	v_mfma_i32_16x16x64_i8 v[8:11], v[154:157], v[200:203], v[8:11]
	v_mfma_i32_16x16x64_i8 v[0:3], v[162:165], v[200:203], v[0:3]
	v_mfma_i32_16x16x64_i8 v[20:23], v[154:157], v[170:173], v[68:71]
	v_mfma_i32_16x16x64_i8 v[32:35], v[162:165], v[170:173], v[64:67]
	v_mfma_i32_16x16x64_i8 v[48:51], v[158:161], v[182:185], v[48:51]
	v_mfma_i32_16x16x64_i8 v[40:43], v[166:169], v[182:185], v[40:43]
	v_mfma_i32_16x16x64_i8 v[28:31], v[158:161], v[194:197], v[28:31]
	v_mfma_i32_16x16x64_i8 v[16:19], v[166:169], v[194:197], v[16:19]
	v_mfma_i32_16x16x64_i8 v[8:11], v[158:161], v[204:207], v[8:11]
	v_mfma_i32_16x16x64_i8 v[0:3], v[166:169], v[204:207], v[0:3]
	v_mfma_i32_16x16x64_i8 v[20:23], v[158:161], v[174:177], v[20:23]
	v_mfma_i32_16x16x64_i8 v[32:35], v[166:169], v[174:177], v[32:35]
	s_barrier
	s_add_i32 s12, 0, 0x18000
	s_add_i32 s13, 0, 0x1c000
	v_add_u32_e32 v68, s12, v198
	v_add_u32_e32 v166, s13, v198
	ds_read_b128 v[56:59], v68
	ds_read_b128 v[60:63], v68 offset:1024
	ds_read_b128 v[64:67], v68 offset:2048
	ds_read_b128 v[68:71], v68 offset:3072
	ds_read_b128 v[154:157], v166
	ds_read_b128 v[158:161], v166 offset:1024
	ds_read_b128 v[162:165], v166 offset:2048
	ds_read_b128 v[166:169], v166 offset:3072
	s_add_u32 s44, s52, 0x80000
	s_addc_u32 s45, s53, 0
	s_mov_b32 m0, s62
	v_lshl_add_u64 v[214:215], s[44:45], 0, v[148:149]
	ds_read_b128 v[170:173], v199 offset:32768
	ds_read_b128 v[174:177], v199 offset:33792
	ds_read_b128 v[178:181], v199 offset:34816
	ds_read_b128 v[182:185], v199 offset:35840
	ds_read_b128 v[186:189], v199 offset:36864
	ds_read_b128 v[194:197], v199 offset:37888
	ds_read_b128 v[200:203], v199 offset:38912
	ds_read_b128 v[204:207], v199 offset:39936
	global_load_lds_dwordx4 v[214:215], off
	v_lshl_add_u64 v[214:215], s[44:45], 0, v[146:147]
	s_mov_b32 m0, s63
	s_nop 0
	global_load_lds_dwordx4 v[214:215], off
	s_waitcnt vmcnt(8)
	s_waitcnt lgkmcnt(0)
	s_barrier
	s_waitcnt lgkmcnt(0)
	v_mfma_i32_16x16x64_i8 v[140:143], v[56:59], v[170:173], v[140:143]
	v_mfma_i32_16x16x64_i8 v[136:139], v[64:67], v[170:173], v[136:139]
	v_mfma_i32_16x16x64_i8 v[132:135], v[56:59], v[178:181], v[132:135]
	v_mfma_i32_16x16x64_i8 v[124:127], v[64:67], v[178:181], v[124:127]
	v_mfma_i32_16x16x64_i8 v[116:119], v[56:59], v[186:189], v[116:119]
	v_mfma_i32_16x16x64_i8 v[108:111], v[64:67], v[186:189], v[108:111]
	v_mfma_i32_16x16x64_i8 v[100:103], v[56:59], v[200:203], v[100:103]
	v_mfma_i32_16x16x64_i8 v[92:95], v[64:67], v[200:203], v[92:95]
	v_mfma_i32_16x16x64_i8 v[140:143], v[60:63], v[174:177], v[140:143]
	v_mfma_i32_16x16x64_i8 v[136:139], v[68:71], v[174:177], v[136:139]
	v_mfma_i32_16x16x64_i8 v[132:135], v[60:63], v[182:185], v[132:135]
	v_mfma_i32_16x16x64_i8 v[124:127], v[68:71], v[182:185], v[124:127]
	v_mfma_i32_16x16x64_i8 v[116:119], v[60:63], v[194:197], v[116:119]
	v_mfma_i32_16x16x64_i8 v[108:111], v[68:71], v[194:197], v[108:111]
	v_mfma_i32_16x16x64_i8 v[100:103], v[60:63], v[204:207], v[100:103]
	v_mfma_i32_16x16x64_i8 v[92:95], v[68:71], v[204:207], v[92:95]
	v_mfma_i32_16x16x64_i8 v[128:131], v[154:157], v[170:173], v[128:131]
	v_mfma_i32_16x16x64_i8 v[120:123], v[162:165], v[170:173], v[120:123]
	v_mfma_i32_16x16x64_i8 v[112:115], v[154:157], v[178:181], v[112:115]
	v_mfma_i32_16x16x64_i8 v[104:107], v[162:165], v[178:181], v[104:107]
	v_mfma_i32_16x16x64_i8 v[96:99], v[154:157], v[186:189], v[96:99]
	v_mfma_i32_16x16x64_i8 v[88:91], v[162:165], v[186:189], v[88:91]
	v_mfma_i32_16x16x64_i8 v[84:87], v[154:157], v[200:203], v[84:87]
	v_mfma_i32_16x16x64_i8 v[80:83], v[162:165], v[200:203], v[80:83]
	v_mfma_i32_16x16x64_i8 v[128:131], v[158:161], v[174:177], v[128:131]
	v_mfma_i32_16x16x64_i8 v[120:123], v[166:169], v[174:177], v[120:123]
	v_mfma_i32_16x16x64_i8 v[112:115], v[158:161], v[182:185], v[112:115]
	v_mfma_i32_16x16x64_i8 v[104:107], v[166:169], v[182:185], v[104:107]
	v_mfma_i32_16x16x64_i8 v[96:99], v[158:161], v[194:197], v[96:99]
	v_mfma_i32_16x16x64_i8 v[88:91], v[166:169], v[194:197], v[88:91]
	v_mfma_i32_16x16x64_i8 v[84:87], v[158:161], v[204:207], v[84:87]
	v_mfma_i32_16x16x64_i8 v[80:83], v[166:169], v[204:207], v[80:83]
	s_barrier
; #define PG8_ITER_HEAD() \
;             const bool last = (t == nt - 2); \
;             const char* a1 = cA + (size_t)(t + 1) * kstep; \
;             const char* a2 = last ? nA : cA + (size_t)(t + 2) * kstep; const char* b2 = last ? nB : cB + (size_t)(t + 2) * kstep; \
;             const char* a3 = a2 + kstep; const char* b3 = b2 + kstep; \
;             if (last && has_next) S.a_ready(nxt);
;     ...
;         int t = 0;
;         if constexpr (SP2 && I8) {
;             for (; t < nt; t += 2) { PG8_ITER_HEAD() PG8_ITER_SP2(PG8_MMAI) }
	s_add_i32 s12, s12, s0
	v_lshl_add_u64 v[190:191], v[190:191], 0, s[34:35]
	s_mov_b32 m0, s12
	ds_read_b128 v[170:173], v199 offset:49152
	ds_read_b128 v[174:177], v199 offset:50176
	ds_read_b128 v[178:181], v199 offset:51200
	ds_read_b128 v[182:185], v199 offset:52224
	ds_read_b128 v[186:189], v199 offset:53248
	ds_read_b128 v[194:197], v199 offset:54272
	ds_read_b128 v[200:203], v199 offset:55296
	ds_read_b128 v[204:207], v199 offset:56320
	global_load_lds_dwordx4 v[190:191], off
	s_add_i32 m0, s12, 0x2000
	s_add_u32 s24, s24, 0x80080
	v_lshl_add_u64 v[190:191], v[208:209], 0, s[34:35]
	s_addc_u32 s25, s25, 0
	s_add_i32 s12, s13, s0
	global_load_lds_dwordx4 v[190:191], off
	v_lshl_add_u64 v[190:191], s[24:25], 0, v[192:193]
	s_mov_b32 m0, s12
	s_nop 0
	global_load_lds_dwordx4 v[190:191], off
	v_lshl_add_u64 v[190:191], s[24:25], 0, v[144:145]
	s_add_i32 m0, s12, 0x2000
	s_nop 0
	global_load_lds_dwordx4 v[190:191], off
	v_lshl_add_u64 v[190:191], v[210:211], 0, s[34:35]
	s_mov_b32 m0, s74
	s_nop 0
	global_load_lds_dwordx4 v[190:191], off
	v_lshl_add_u64 v[190:191], v[212:213], 0, s[34:35]
	s_mov_b32 m0, s75
	s_nop 0
	global_load_lds_dwordx4 v[190:191], off
	s_waitcnt vmcnt(8)
	s_waitcnt lgkmcnt(0)
	s_barrier
	s_waitcnt lgkmcnt(0)
	v_mfma_i32_16x16x64_i8 v[76:79], v[56:59], v[170:173], v[76:79]
	v_mfma_i32_16x16x64_i8 v[72:75], v[64:67], v[170:173], v[72:75]
	v_mfma_i32_16x16x64_i8 v[52:55], v[56:59], v[178:181], v[52:55]
	v_mfma_i32_16x16x64_i8 v[44:47], v[64:67], v[178:181], v[44:47]
	v_mfma_i32_16x16x64_i8 v[36:39], v[56:59], v[186:189], v[36:39]
	v_mfma_i32_16x16x64_i8 v[24:27], v[64:67], v[186:189], v[24:27]
	v_mfma_i32_16x16x64_i8 v[12:15], v[56:59], v[200:203], v[12:15]
	v_mfma_i32_16x16x64_i8 v[4:7], v[64:67], v[200:203], v[4:7]
	v_mfma_i32_16x16x64_i8 v[76:79], v[60:63], v[174:177], v[76:79]
	v_mfma_i32_16x16x64_i8 v[72:75], v[68:71], v[174:177], v[72:75]
	v_mfma_i32_16x16x64_i8 v[52:55], v[60:63], v[182:185], v[52:55]
	v_mfma_i32_16x16x64_i8 v[44:47], v[68:71], v[182:185], v[44:47]
	v_mfma_i32_16x16x64_i8 v[36:39], v[60:63], v[194:197], v[36:39]
	v_mfma_i32_16x16x64_i8 v[24:27], v[68:71], v[194:197], v[24:27]
	v_mfma_i32_16x16x64_i8 v[12:15], v[60:63], v[204:207], v[12:15]
	v_mfma_i32_16x16x64_i8 v[4:7], v[68:71], v[204:207], v[4:7]
	v_mfma_i32_16x16x64_i8 v[20:23], v[154:157], v[170:173], v[20:23]
	v_mfma_i32_16x16x64_i8 v[68:71], v[158:161], v[174:177], v[20:23]
	v_mfma_i32_16x16x64_i8 v[20:23], v[162:165], v[170:173], v[32:35]
	v_mfma_i32_16x16x64_i8 v[64:67], v[166:169], v[174:177], v[20:23]
	v_mfma_i32_16x16x64_i8 v[20:23], v[154:157], v[178:181], v[48:51]
	v_mfma_i32_16x16x64_i8 v[48:51], v[158:161], v[182:185], v[20:23]
	v_mfma_i32_16x16x64_i8 v[20:23], v[162:165], v[178:181], v[40:43]
	v_mfma_i32_16x16x64_i8 v[40:43], v[166:169], v[182:185], v[20:23]
	v_mfma_i32_16x16x64_i8 v[20:23], v[154:157], v[186:189], v[28:31]
	v_mfma_i32_16x16x64_i8 v[16:19], v[162:165], v[186:189], v[16:19]
	v_mfma_i32_16x16x64_i8 v[8:11], v[154:157], v[200:203], v[8:11]
	v_mfma_i32_16x16x64_i8 v[0:3], v[162:165], v[200:203], v[0:3]
	v_mfma_i32_16x16x64_i8 v[28:31], v[158:161], v[194:197], v[20:23]
	v_mfma_i32_16x16x64_i8 v[16:19], v[166:169], v[194:197], v[16:19]
	v_mfma_i32_16x16x64_i8 v[8:11], v[158:161], v[204:207], v[8:11]
	v_mfma_i32_16x16x64_i8 v[0:3], v[166:169], v[204:207], v[0:3]
	s_barrier
	s_add_i32 s29, s29, 2
	s_add_u32 s50, s50, 0x100
	s_addc_u32 s51, s51, 0
	s_add_u32 s10, s10, 0x100
	s_addc_u32 s11, s11, 0
	s_cmp_lt_u32 s29, 30
	s_cbranch_scc1 .LBB0_552
	s_andn2_b64 vcc, exec, s[38:39]
	s_cbranch_vccnz .LBB0_555
	s_barrier

; #define PG8_BAR __builtin_amdgcn_s_barrier()
;     ...
;     const int wid = __builtin_amdgcn_readfirstlane(tid >> 6), lane = tid & 63, wr = wid >> 2, wc = wid & 3, fr = lane & 15, fq = lane >> 4;
;     const int K = g.K, nt = K / BK;
;     unsigned voffA[2], voffB[2];
; #pragma unroll
;     for (int i = 0; i < 2; ++i) { int R, C; stage_rc(tid * 16 + i * 8192, R, C); const int Rb = Epi::PERM ? ((R & ~31) + perm32(R & 31)) : R;
;         voffA[i] = (unsigned)(R * K + C) * 2u; voffB[i] = (unsigned)(Rb * K + C) * 2u; }
;     const size_t kstep = (size_t)(BK * 2);
;     const size_t hstep = (size_t)HALF * K * 2;
;     const size_t tstep = 2 * hstep;
;     const unsigned ldsw = (unsigned)wid * 1024u;
;     const int aoff = lds_byte(wr * 64 + fr, fq * 8), boff = lds_byte(wc * 32 + fr, fq * 8);
;     ...
;     Unit cur, nxt; int ui = 0;
;     if (!S.next(0, cur)) return;
;     f32x4 acc[2][2][4][2];
; #pragma unroll
;     for (int a = 0; a < 2; ++a)
; #pragma unroll
;         for (int b = 0; b < 2; ++b)
; #pragma unroll
;             for (int m = 0; m < 4; ++m)
; #pragma unroll
;                 for (int n = 0; n < 2; ++n) acc[a][b][m][n] = (f32x4){0.f, 0.f, 0.f, 0.f};
;     bf16x8 At[4][2], B0[2][2], B1[2][2];
;     const char* cA = (const char*)g.A + (size_t)cur.pm * tstep; const char* cB = (const char*)g.Bt + (size_t)cur.pn * tstep;
;     S.a_ready(cur);
;     if constexpr (SP2) {
;         PG8_STAGE(PG8_SB(0, 0), cB, voffB); PG8_STAGE(PG8_SB(0, 1), cB + hstep, voffB); PG8_STAGE(PG8_SA(0, 0), cA, voffA); PG8_STAGE(PG8_SA(0, 1), cA + hstep, voffA);
;         if (wr == 1) PG8_BAR;
.LBB0_598:
	s_or_b64 exec, exec, s[28:29]
	s_waitcnt lgkmcnt(0)
	s_barrier
	v_mbcnt_lo_u32_b32 v0, -1, 0
	v_mbcnt_hi_u32_b32 v0, -1, v0
	v_readlane_b32 s4, v255, 39
	v_add_u32_e32 v0, s59, v0
	v_readlane_b32 s5, v255, 40
	s_and_b64 vcc, exec, s[4:5]
	v_readfirstlane_b32 s8, v0
	s_cbranch_vccnz .LBB0_624
	v_bfe_i32 v3, v0, 27, 1
	v_lshlrev_b32_e32 v1, 4, v0
	v_lshrrev_b32_e32 v3, 22, v3
	v_add_u32_e32 v3, v1, v3
	v_and_b32_e32 v3, 0xfffffc00, v3
	v_sub_u32_e32 v3, v1, v3
	v_ashrrev_i32_e32 v2, 31, v0
	v_lshrrev_b32_e32 v4, 4, v3
	v_lshrrev_b32_e32 v2, 26, v2
	v_bitop3_b32 v3, v4, v3, 32 bitop3:0x6c
	v_add_u32_e32 v2, v0, v2
	v_ashrrev_i32_e32 v5, 31, v3
	v_ashrrev_i32_e32 v2, 6, v2
	v_lshrrev_b32_e32 v5, 26, v5
	v_lshlrev_b32_e32 v4, 3, v2
	v_add_u32_e32 v5, v3, v5
	v_and_b32_e32 v4, 0x1fffff0, v4
	v_lshrrev_b32_e32 v6, 6, v5
	v_and_b32_e32 v5, 0xc0, v5
	v_add_u32_e32 v4, v6, v4
	v_sub_u32_e32 v3, v3, v5
	s_movk_i32 s0, 0x1880
	v_lshlrev_b32_e32 v2, 5, v2
	v_ashrrev_i16_sdwa v3, v251, sext(v3) dst_sel:DWORD dst_unused:UNUSED_PAD src0_sel:DWORD src1_sel:BYTE_0
	v_mul_lo_u32 v4, v4, s0
	v_bfe_i32 v3, v3, 0, 16
	v_and_or_b32 v2, v2, 32, v4
	v_add_u32_e32 v1, 0x2000, v1
	v_add_lshl_u32 v130, v2, v3, 1
	v_ashrrev_i32_e32 v2, 31, v1
	v_lshrrev_b32_e32 v2, 22, v2
	v_add_u32_e32 v2, v1, v2
	v_ashrrev_i32_e32 v2, 10, v2
	v_mul_i32_i24_e32 v3, 0x400, v2
	v_sub_u32_e32 v1, v1, v3
	v_lshrrev_b32_e32 v3, 4, v1
	v_bitop3_b32 v1, v3, v1, 32 bitop3:0x6c
	v_ashrrev_i32_e32 v4, 31, v1
	v_lshrrev_b32_e32 v4, 26, v4
	v_lshlrev_b32_e32 v3, 3, v2
	v_add_u32_e32 v4, v1, v4
	v_and_b32_e32 v3, 0x1fffff0, v3
	v_lshrrev_b32_e32 v5, 6, v4
	v_add_u32_e32 v3, v5, v3
	v_and_b32_e32 v4, 0xc0, v4
	s_ashr_i32 s10, s8, 6
	v_sub_u32_e32 v1, v1, v4
	v_mul_lo_u32 v3, v3, s0
	s_lshl_b32 s0, s10, 10
	v_lshlrev_b32_e32 v2, 5, v2
	v_ashrrev_i16_sdwa v1, v251, sext(v1) dst_sel:DWORD dst_unused:UNUSED_PAD src0_sel:DWORD src1_sel:BYTE_0
	s_add_i32 s0, s0, 0
	v_readlane_b32 s12, v254, 29
	v_bfe_i32 v1, v1, 0, 16
	v_and_or_b32 v2, v2, 32, v3
	s_add_i32 s4, s0, 0x10000
	v_readlane_b32 s13, v254, 30
	s_mov_b32 s5, m0
	s_mov_b32 m0, s4
	s_nop 0
	global_load_lds_dwordx4 v130, s[12:13]
	s_mov_b32 m0, s5
	v_add_lshl_u32 v131, v2, v1, 1
	s_add_i32 s5, s0, 0x12000
	s_mov_b32 s6, m0
	s_mov_b32 m0, s5
	s_nop 0
	global_load_lds_dwordx4 v131, s[12:13]
	s_mov_b32 m0, s6
	v_readlane_b32 s12, v254, 17
	s_add_i32 s6, s0, 0x14000
	v_readlane_b32 s13, v254, 18
	s_mov_b32 s7, m0
	s_mov_b32 m0, s6
	s_nop 0
	global_load_lds_dwordx4 v130, s[12:13]
	s_mov_b32 m0, s7
	s_add_i32 s7, s0, 0x16000
	s_mov_b32 s11, m0
	s_mov_b32 m0, s7
	s_nop 0
	global_load_lds_dwordx4 v131, s[12:13]
	s_mov_b32 m0, s11
	v_readlane_b32 s12, v254, 25
	v_readlane_b32 s13, v254, 26
	s_mov_b32 s11, m0
	s_mov_b32 m0, s0
	s_nop 0
	global_load_lds_dwordx4 v130, s[12:13]
	s_mov_b32 m0, s11
	s_add_i32 s44, s0, 0x2000
	s_mov_b32 s11, m0
	s_mov_b32 m0, s44
	s_nop 0
	global_load_lds_dwordx4 v131, s[12:13]
	s_mov_b32 m0, s11
	v_readlane_b32 s12, v254, 21
	s_add_i32 s45, s0, 0x4000
	v_readlane_b32 s13, v254, 22
	s_mov_b32 s11, m0
	s_mov_b32 m0, s45
	s_nop 0
	global_load_lds_dwordx4 v130, s[12:13]
	s_mov_b32 m0, s11
	s_ashr_i32 s9, s8, 8
	s_add_i32 s58, s0, 0x6000
	s_mov_b32 s11, m0
	s_mov_b32 m0, s58
	s_nop 0
	global_load_lds_dwordx4 v131, s[12:13]
	s_mov_b32 m0, s11
	s_cmp_eq_u32 s9, 1
	s_cselect_b64 s[28:29], -1, 0
	s_cmp_lg_u32 s9, 1
	s_cbranch_scc1 .LBB0_601
	s_barrier
	s_setprio 1

.LBB0_615:
	v_add_u32_e32 v128, 0x10000, v132
	v_add_u32_e32 v129, 0x14000, v132
	ds_read_b128 v[134:137], v128
	ds_read_b128 v[138:141], v128 offset:1024
	ds_read_b128 v[142:145], v128 offset:2048
	ds_read_b128 v[146:149], v128 offset:3072
	ds_read_b128 v[150:153], v129
	ds_read_b128 v[154:157], v129 offset:1024
	ds_read_b128 v[158:161], v129 offset:2048
	ds_read_b128 v[162:165], v129 offset:3072
	s_add_u32 s94, s60, 0x180
	s_addc_u32 s95, s61, 0
	s_add_u32 s62, s56, 0x100
	s_addc_u32 s63, s57, 0
	s_add_u32 s90, s60, 0x100
	s_addc_u32 s91, s61, 0
	ds_read_b128 v[166:169], v133
	ds_read_b128 v[170:173], v133 offset:1024
	ds_read_b128 v[174:177], v133 offset:2048
	ds_read_b128 v[178:181], v133 offset:3072
	ds_read_b128 v[182:185], v133 offset:4096
	ds_read_b128 v[186:189], v133 offset:5120
	ds_read_b128 v[194:197], v133 offset:6144
	ds_read_b128 v[198:201], v133 offset:7168
	s_add_u32 s12, s60, 0x188080
	s_addc_u32 s13, s61, 0
	s_mov_b32 s25, m0
	s_mov_b32 m0, s79
	s_nop 0
	global_load_lds_dwordx4 v130, s[12:13]
	s_mov_b32 m0, s25
	s_nop 0
	s_mov_b32 s25, m0
	s_mov_b32 m0, s96
	s_nop 0
	global_load_lds_dwordx4 v131, s[12:13]
	s_mov_b32 m0, s25
	s_waitcnt vmcnt(8)
	s_waitcnt lgkmcnt(0)
	s_barrier
	s_waitcnt lgkmcnt(0)
	v_mfma_f32_16x16x32_bf16 v[124:127], v[134:137], v[166:169], v[124:127]
	v_mfma_f32_16x16x32_bf16 v[120:123], v[142:145], v[166:169], v[120:123]
	v_mfma_f32_16x16x32_bf16 v[112:115], v[134:137], v[174:177], v[112:115]
	v_mfma_f32_16x16x32_bf16 v[104:107], v[142:145], v[174:177], v[104:107]
	v_mfma_f32_16x16x32_bf16 v[96:99], v[134:137], v[182:185], v[96:99]
	v_mfma_f32_16x16x32_bf16 v[88:91], v[142:145], v[182:185], v[88:91]
	v_mfma_f32_16x16x32_bf16 v[80:83], v[134:137], v[194:197], v[80:83]
	v_mfma_f32_16x16x32_bf16 v[72:75], v[142:145], v[194:197], v[72:75]
	v_mfma_f32_16x16x32_bf16 v[124:127], v[138:141], v[170:173], v[124:127]
	v_mfma_f32_16x16x32_bf16 v[120:123], v[146:149], v[170:173], v[120:123]
	v_mfma_f32_16x16x32_bf16 v[112:115], v[138:141], v[178:181], v[112:115]
	v_mfma_f32_16x16x32_bf16 v[104:107], v[146:149], v[178:181], v[104:107]
	v_mfma_f32_16x16x32_bf16 v[96:99], v[138:141], v[186:189], v[96:99]
	v_mfma_f32_16x16x32_bf16 v[88:91], v[146:149], v[186:189], v[88:91]
	v_mfma_f32_16x16x32_bf16 v[80:83], v[138:141], v[198:201], v[80:83]
	v_mfma_f32_16x16x32_bf16 v[72:75], v[146:149], v[198:201], v[72:75]
	v_mfma_f32_16x16x32_bf16 v[116:119], v[150:153], v[166:169], v[116:119]
	v_mfma_f32_16x16x32_bf16 v[108:111], v[158:161], v[166:169], v[108:111]
	v_mfma_f32_16x16x32_bf16 v[100:103], v[150:153], v[174:177], v[100:103]
	v_mfma_f32_16x16x32_bf16 v[92:95], v[158:161], v[174:177], v[92:95]
	v_mfma_f32_16x16x32_bf16 v[84:87], v[150:153], v[182:185], v[84:87]
	v_mfma_f32_16x16x32_bf16 v[76:79], v[158:161], v[182:185], v[76:79]
	v_mfma_f32_16x16x32_bf16 v[68:71], v[150:153], v[194:197], v[68:71]
	v_mfma_f32_16x16x32_bf16 v[64:67], v[158:161], v[194:197], v[64:67]
	v_mfma_f32_16x16x32_bf16 v[116:119], v[154:157], v[170:173], v[116:119]
	v_mfma_f32_16x16x32_bf16 v[108:111], v[162:165], v[170:173], v[108:111]
	v_mfma_f32_16x16x32_bf16 v[100:103], v[154:157], v[178:181], v[100:103]
	v_mfma_f32_16x16x32_bf16 v[92:95], v[162:165], v[178:181], v[92:95]
	v_mfma_f32_16x16x32_bf16 v[84:87], v[154:157], v[186:189], v[84:87]
	v_mfma_f32_16x16x32_bf16 v[76:79], v[162:165], v[186:189], v[76:79]
	v_mfma_f32_16x16x32_bf16 v[68:71], v[154:157], v[198:201], v[68:71]
	v_mfma_f32_16x16x32_bf16 v[64:67], v[162:165], v[198:201], v[64:67]
	s_barrier
	ds_read_b128 v[166:169], v133 offset:16384
	ds_read_b128 v[170:173], v133 offset:17408
	ds_read_b128 v[174:177], v133 offset:18432
	ds_read_b128 v[178:181], v133 offset:19456
	ds_read_b128 v[182:185], v133 offset:20480
	ds_read_b128 v[186:189], v133 offset:21504
	ds_read_b128 v[194:197], v133 offset:22528
	ds_read_b128 v[198:201], v133 offset:23552
	s_mov_b32 s12, m0
	s_mov_b32 m0, s4
	s_nop 0
	global_load_lds_dwordx4 v130, s[62:63]
	s_mov_b32 m0, s12
	s_nop 0
	s_mov_b32 s12, m0
	s_mov_b32 m0, s5
	s_nop 0
	global_load_lds_dwordx4 v131, s[62:63]
	s_mov_b32 m0, s12
	s_add_u32 s12, s56, 0x188100
	s_addc_u32 s13, s57, 0
	s_mov_b32 s25, m0
	s_mov_b32 m0, s6
	s_nop 0
	global_load_lds_dwordx4 v130, s[12:13]
	s_mov_b32 m0, s25
	s_nop 0
	s_mov_b32 s25, m0
	s_mov_b32 m0, s7
	s_nop 0
	global_load_lds_dwordx4 v131, s[12:13]
	s_mov_b32 m0, s25
	s_mov_b32 s12, m0
	s_mov_b32 m0, s0
	s_nop 0
	global_load_lds_dwordx4 v130, s[90:91]
	s_mov_b32 m0, s12
	s_nop 0
	s_mov_b32 s12, m0
	s_mov_b32 m0, s44
	s_nop 0
	global_load_lds_dwordx4 v131, s[90:91]
	s_mov_b32 m0, s12
	s_waitcnt vmcnt(8)
	s_waitcnt lgkmcnt(0)
	s_barrier
	s_waitcnt lgkmcnt(0)
	v_mfma_f32_16x16x32_bf16 v[60:63], v[134:137], v[166:169], v[60:63]
	v_mfma_f32_16x16x32_bf16 v[56:59], v[142:145], v[166:169], v[56:59]
	v_mfma_f32_16x16x32_bf16 v[52:55], v[134:137], v[174:177], v[52:55]
	v_mfma_f32_16x16x32_bf16 v[40:43], v[142:145], v[174:177], v[40:43]
	v_mfma_f32_16x16x32_bf16 v[36:39], v[134:137], v[182:185], v[36:39]
	v_mfma_f32_16x16x32_bf16 v[24:27], v[142:145], v[182:185], v[24:27]
	v_mfma_f32_16x16x32_bf16 v[20:23], v[134:137], v[194:197], v[20:23]
	v_mfma_f32_16x16x32_bf16 v[8:11], v[142:145], v[194:197], v[8:11]
	v_mfma_f32_16x16x32_bf16 v[60:63], v[138:141], v[170:173], v[60:63]
	v_mfma_f32_16x16x32_bf16 v[56:59], v[146:149], v[170:173], v[56:59]
	v_mfma_f32_16x16x32_bf16 v[52:55], v[138:141], v[178:181], v[52:55]
	v_mfma_f32_16x16x32_bf16 v[40:43], v[146:149], v[178:181], v[40:43]
	v_mfma_f32_16x16x32_bf16 v[36:39], v[138:141], v[186:189], v[36:39]
	v_mfma_f32_16x16x32_bf16 v[24:27], v[146:149], v[186:189], v[24:27]
	v_mfma_f32_16x16x32_bf16 v[20:23], v[138:141], v[198:201], v[20:23]
	v_mfma_f32_16x16x32_bf16 v[8:11], v[146:149], v[198:201], v[8:11]
	v_mfma_f32_16x16x32_bf16 v[48:51], v[150:153], v[166:169], v[48:51]
	v_mfma_f32_16x16x32_bf16 v[44:47], v[158:161], v[166:169], v[44:47]
	v_mfma_f32_16x16x32_bf16 v[32:35], v[150:153], v[174:177], v[32:35]
	v_mfma_f32_16x16x32_bf16 v[28:31], v[158:161], v[174:177], v[28:31]
	v_mfma_f32_16x16x32_bf16 v[16:19], v[150:153], v[182:185], v[16:19]
	v_mfma_f32_16x16x32_bf16 v[12:15], v[158:161], v[182:185], v[12:15]
	v_mfma_f32_16x16x32_bf16 v[4:7], v[150:153], v[194:197], v[4:7]
	v_mfma_f32_16x16x32_bf16 v[0:3], v[158:161], v[194:197], v[0:3]
	v_mfma_f32_16x16x32_bf16 v[48:51], v[154:157], v[170:173], v[48:51]
	v_mfma_f32_16x16x32_bf16 v[44:47], v[162:165], v[170:173], v[44:47]
	v_mfma_f32_16x16x32_bf16 v[32:35], v[154:157], v[178:181], v[32:35]
	v_mfma_f32_16x16x32_bf16 v[28:31], v[162:165], v[178:181], v[28:31]
	v_mfma_f32_16x16x32_bf16 v[16:19], v[154:157], v[186:189], v[16:19]
	v_mfma_f32_16x16x32_bf16 v[12:15], v[162:165], v[186:189], v[12:15]
	v_mfma_f32_16x16x32_bf16 v[4:7], v[154:157], v[198:201], v[4:7]
	v_mfma_f32_16x16x32_bf16 v[0:3], v[162:165], v[198:201], v[0:3]
	s_barrier
	v_add_u32_e32 v134, 0x18000, v132
	v_add_u32_e32 v135, 0x1c000, v132
	ds_read_b128 v[136:139], v134
	ds_read_b128 v[140:143], v134 offset:1024
	ds_read_b128 v[144:147], v134 offset:2048
	ds_read_b128 v[148:151], v134 offset:3072
	ds_read_b128 v[152:155], v135
	ds_read_b128 v[156:159], v135 offset:1024
	ds_read_b128 v[160:163], v135 offset:2048
	ds_read_b128 v[164:167], v135 offset:3072
	ds_read_b128 v[168:171], v133 offset:32768
	ds_read_b128 v[172:175], v133 offset:33792
	ds_read_b128 v[176:179], v133 offset:34816
	ds_read_b128 v[180:183], v133 offset:35840
	ds_read_b128 v[184:187], v133 offset:36864
	ds_read_b128 v[188:191], v133 offset:37888
	ds_read_b128 v[194:197], v133 offset:38912
	ds_read_b128 v[198:201], v133 offset:39936
	s_add_u32 s12, s60, 0x188100
	s_addc_u32 s13, s61, 0
	s_mov_b32 s25, m0
	s_mov_b32 m0, s45
	s_nop 0
	global_load_lds_dwordx4 v130, s[12:13]
	s_mov_b32 m0, s25
	s_nop 0
	s_mov_b32 s25, m0
	s_mov_b32 m0, s58
	s_nop 0
	global_load_lds_dwordx4 v131, s[12:13]
	s_mov_b32 m0, s25
	s_waitcnt vmcnt(8)
	s_waitcnt lgkmcnt(0)
	s_barrier
	s_waitcnt lgkmcnt(0)
	v_mfma_f32_16x16x32_bf16 v[124:127], v[136:139], v[168:171], v[124:127]
	v_mfma_f32_16x16x32_bf16 v[120:123], v[144:147], v[168:171], v[120:123]
	v_mfma_f32_16x16x32_bf16 v[112:115], v[136:139], v[176:179], v[112:115]
	v_mfma_f32_16x16x32_bf16 v[104:107], v[144:147], v[176:179], v[104:107]
	v_mfma_f32_16x16x32_bf16 v[96:99], v[136:139], v[184:187], v[96:99]
	v_mfma_f32_16x16x32_bf16 v[88:91], v[144:147], v[184:187], v[88:91]
	v_mfma_f32_16x16x32_bf16 v[80:83], v[136:139], v[194:197], v[80:83]
	v_mfma_f32_16x16x32_bf16 v[72:75], v[144:147], v[194:197], v[72:75]
	v_mfma_f32_16x16x32_bf16 v[124:127], v[140:143], v[172:175], v[124:127]
	v_mfma_f32_16x16x32_bf16 v[120:123], v[148:151], v[172:175], v[120:123]
	v_mfma_f32_16x16x32_bf16 v[112:115], v[140:143], v[180:183], v[112:115]
	v_mfma_f32_16x16x32_bf16 v[104:107], v[148:151], v[180:183], v[104:107]
	v_mfma_f32_16x16x32_bf16 v[96:99], v[140:143], v[188:191], v[96:99]
	v_mfma_f32_16x16x32_bf16 v[88:91], v[148:151], v[188:191], v[88:91]
	v_mfma_f32_16x16x32_bf16 v[80:83], v[140:143], v[198:201], v[80:83]
	v_mfma_f32_16x16x32_bf16 v[72:75], v[148:151], v[198:201], v[72:75]
	v_mfma_f32_16x16x32_bf16 v[116:119], v[152:155], v[168:171], v[116:119]
	v_mfma_f32_16x16x32_bf16 v[108:111], v[160:163], v[168:171], v[108:111]
	v_mfma_f32_16x16x32_bf16 v[100:103], v[152:155], v[176:179], v[100:103]
	v_mfma_f32_16x16x32_bf16 v[92:95], v[160:163], v[176:179], v[92:95]
	v_mfma_f32_16x16x32_bf16 v[84:87], v[152:155], v[184:187], v[84:87]
	v_mfma_f32_16x16x32_bf16 v[76:79], v[160:163], v[184:187], v[76:79]
	v_mfma_f32_16x16x32_bf16 v[68:71], v[152:155], v[194:197], v[68:71]
	v_mfma_f32_16x16x32_bf16 v[64:67], v[160:163], v[194:197], v[64:67]
	v_mfma_f32_16x16x32_bf16 v[116:119], v[156:159], v[172:175], v[116:119]
	v_mfma_f32_16x16x32_bf16 v[108:111], v[164:167], v[172:175], v[108:111]
	v_mfma_f32_16x16x32_bf16 v[100:103], v[156:159], v[180:183], v[100:103]
	v_mfma_f32_16x16x32_bf16 v[92:95], v[164:167], v[180:183], v[92:95]
	v_mfma_f32_16x16x32_bf16 v[84:87], v[156:159], v[188:191], v[84:87]
	v_mfma_f32_16x16x32_bf16 v[76:79], v[164:167], v[188:191], v[76:79]
	v_mfma_f32_16x16x32_bf16 v[68:71], v[156:159], v[198:201], v[68:71]
	v_mfma_f32_16x16x32_bf16 v[64:67], v[164:167], v[198:201], v[64:67]
	s_barrier
; #define PG8_MMA(ai, bj, At, Bt) do { __builtin_amdgcn_s_setprio(1); _Pragma("unroll") for (int m = 0; m < 4; ++m) _Pragma("unroll") for (int n = 0; n < 2; ++n) _Pragma("unroll") for (int k = 0; k < 2; ++k) \
;         acc[ai][bj][m][n] = __builtin_amdgcn_mfma_f32_16x16x32_bf16(Bt[n][k], At[m][k], acc[ai][bj][m][n], 0, 0, 0); __builtin_amdgcn_s_setprio(0); } while (0)
; #define PG8_MMA8(ai, bj, At, Bt) do { __builtin_amdgcn_s_setprio(1); _Pragma("unroll") for (int m = 0; m < 4; ++m) _Pragma("unroll") for (int n = 0; n < 2; ++n) \
;         acc[ai][bj][m][n] = __builtin_amdgcn_mfma_scale_f32_16x16x128_f8f6f4(cat8(Bt[n][0], Bt[n][1]), cat8(At[m][0], At[m][1]), acc[ai][bj][m][n], 0, 0, 0, F8_SC_W, 0, F8_SC_H); __builtin_amdgcn_s_setprio(0); } while (0)
; #define PG8_ITER_HEAD() \
;             const bool last = (t == nt - 2); \
;             const char* a1 = cA + (size_t)(t + 1) * kstep; \
;             const char* a2 = last ? nA : cA + (size_t)(t + 2) * kstep; const char* b2 = last ? nB : cB + (size_t)(t + 2) * kstep; \
;             const char* a3 = a2 + kstep; const char* b3 = b2 + kstep; \
;             if (last && has_next) S.a_ready(nxt);
;     ...
;         int t = 0;
;         if constexpr (SP2 && I8) {
;             for (; t < nt; t += 2) { PG8_ITER_HEAD() PG8_ITER_SP2(PG8_MMAI) }
;         } else if constexpr (SP2 && KS8 > 0) {
;             for (; t < KS8; t += 2) { PG8_ITER_HEAD() PG8_ITER_SP2(PG8_MMA) }
;             for (; t < nt; t += 2) { PG8_ITER_HEAD() PG8_ITER_SP2(PG8_MMA8) }
	ds_read_b128 v[168:171], v133 offset:49152
	ds_read_b128 v[172:175], v133 offset:50176
	ds_read_b128 v[176:179], v133 offset:51200
	ds_read_b128 v[180:183], v133 offset:52224
	ds_read_b128 v[184:187], v133 offset:53248
	ds_read_b128 v[188:191], v133 offset:54272
	ds_read_b128 v[194:197], v133 offset:55296
	ds_read_b128 v[198:201], v133 offset:56320
	s_add_u32 s12, s56, 0x180
	s_addc_u32 s13, s57, 0
	s_mov_b32 s25, m0
	s_mov_b32 m0, s73
	s_nop 0
	global_load_lds_dwordx4 v130, s[12:13]
	s_mov_b32 m0, s25
	s_nop 0
	s_mov_b32 s25, m0
	s_mov_b32 m0, s74
	s_nop 0
	global_load_lds_dwordx4 v131, s[12:13]
	s_mov_b32 m0, s25
	s_add_u32 s12, s56, 0x188180
	s_addc_u32 s13, s57, 0
	s_mov_b32 s25, m0
	s_mov_b32 m0, s77
	s_nop 0
	global_load_lds_dwordx4 v130, s[12:13]
	s_mov_b32 m0, s25
	s_nop 0
	s_mov_b32 s25, m0
	s_mov_b32 m0, s78
	s_nop 0
	global_load_lds_dwordx4 v131, s[12:13]
	s_mov_b32 m0, s25
	s_mov_b32 s12, m0
	s_mov_b32 m0, s75
	s_nop 0
	global_load_lds_dwordx4 v130, s[94:95]
	s_mov_b32 m0, s12
	s_nop 0
	s_mov_b32 s12, m0
	s_mov_b32 m0, s76
	s_nop 0
	global_load_lds_dwordx4 v131, s[94:95]
	s_mov_b32 m0, s12
	s_waitcnt vmcnt(8)
	s_waitcnt lgkmcnt(0)
	s_barrier
	s_waitcnt lgkmcnt(0)
	v_mfma_f32_16x16x32_bf16 v[60:63], v[136:139], v[168:171], v[60:63]
	v_mfma_f32_16x16x32_bf16 v[56:59], v[144:147], v[168:171], v[56:59]
	v_mfma_f32_16x16x32_bf16 v[52:55], v[136:139], v[176:179], v[52:55]
	v_mfma_f32_16x16x32_bf16 v[40:43], v[144:147], v[176:179], v[40:43]
	v_mfma_f32_16x16x32_bf16 v[36:39], v[136:139], v[184:187], v[36:39]
	v_mfma_f32_16x16x32_bf16 v[24:27], v[144:147], v[184:187], v[24:27]
	v_mfma_f32_16x16x32_bf16 v[20:23], v[136:139], v[194:197], v[20:23]
	v_mfma_f32_16x16x32_bf16 v[8:11], v[144:147], v[194:197], v[8:11]
	v_mfma_f32_16x16x32_bf16 v[60:63], v[140:143], v[172:175], v[60:63]
	v_mfma_f32_16x16x32_bf16 v[56:59], v[148:151], v[172:175], v[56:59]
	v_mfma_f32_16x16x32_bf16 v[52:55], v[140:143], v[180:183], v[52:55]
	v_mfma_f32_16x16x32_bf16 v[40:43], v[148:151], v[180:183], v[40:43]
	v_mfma_f32_16x16x32_bf16 v[36:39], v[140:143], v[188:191], v[36:39]
	v_mfma_f32_16x16x32_bf16 v[24:27], v[148:151], v[188:191], v[24:27]
	v_mfma_f32_16x16x32_bf16 v[20:23], v[140:143], v[198:201], v[20:23]
	v_mfma_f32_16x16x32_bf16 v[8:11], v[148:151], v[198:201], v[8:11]
	v_mfma_f32_16x16x32_bf16 v[48:51], v[152:155], v[168:171], v[48:51]
	v_mfma_f32_16x16x32_bf16 v[44:47], v[160:163], v[168:171], v[44:47]
	v_mfma_f32_16x16x32_bf16 v[32:35], v[152:155], v[176:179], v[32:35]
	v_mfma_f32_16x16x32_bf16 v[28:31], v[160:163], v[176:179], v[28:31]
	v_mfma_f32_16x16x32_bf16 v[16:19], v[152:155], v[184:187], v[16:19]
	v_mfma_f32_16x16x32_bf16 v[12:15], v[160:163], v[184:187], v[12:15]
	v_mfma_f32_16x16x32_bf16 v[4:7], v[152:155], v[194:197], v[4:7]
	v_mfma_f32_16x16x32_bf16 v[0:3], v[160:163], v[194:197], v[0:3]
	v_mfma_f32_16x16x32_bf16 v[48:51], v[156:159], v[172:175], v[48:51]
	v_mfma_f32_16x16x32_bf16 v[44:47], v[164:167], v[172:175], v[44:47]
	v_mfma_f32_16x16x32_bf16 v[32:35], v[156:159], v[180:183], v[32:35]
	v_mfma_f32_16x16x32_bf16 v[28:31], v[164:167], v[180:183], v[28:31]
	v_mfma_f32_16x16x32_bf16 v[16:19], v[156:159], v[188:191], v[16:19]
	v_mfma_f32_16x16x32_bf16 v[12:15], v[164:167], v[188:191], v[12:15]
	v_mfma_f32_16x16x32_bf16 v[4:7], v[156:159], v[198:201], v[4:7]
	v_mfma_f32_16x16x32_bf16 v[0:3], v[164:167], v[198:201], v[0:3]
	s_barrier
	s_add_i32 s24, s24, 2
	s_cmp_lt_u32 s24, 22
	s_mov_b64 s[56:57], s[62:63]
	s_mov_b64 s[60:61], s[90:91]
	s_cbranch_scc1 .LBB0_615
	s_add_u32 s60, s52, 0xc00
	s_addc_u32 s61, s53, 0
	s_add_u32 s62, s50, 0xd00
	s_addc_u32 s63, s51, 0
	s_mov_b32 s90, 22
.LBB0_617:
	ds_read_b128 v[136:139], v128
	ds_read_b128 v[140:143], v128 offset:1024
	ds_read_b128 v[144:147], v128 offset:2048
	ds_read_b128 v[148:151], v128 offset:3072
	ds_read_b128 v[152:155], v129
	ds_read_b128 v[156:159], v129 offset:1024
	ds_read_b128 v[160:163], v129 offset:2048
	ds_read_b128 v[164:167], v129 offset:3072
	s_add_u32 s50, s60, 0x100
	s_addc_u32 s51, s61, 0
	s_cmpk_eq_i32 s90, 0x5e
	s_cselect_b32 s24, s40, s50
	s_cselect_b32 s25, s41, s51
	s_cselect_b32 s56, s46, s62
	s_cselect_b32 s57, s47, s63
	s_add_u32 s52, s24, 0x80
	s_addc_u32 s53, s25, 0
	ds_read_b128 v[168:171], v133
	ds_read_b128 v[172:175], v133 offset:1024
	ds_read_b128 v[176:179], v133 offset:2048
	ds_read_b128 v[180:183], v133 offset:3072
	ds_read_b128 v[184:187], v133 offset:4096
	ds_read_b128 v[188:191], v133 offset:5120
	ds_read_b128 v[198:201], v133 offset:6144
	ds_read_b128 v[202:205], v133 offset:7168
	s_add_u32 s12, s60, 0x188080
	s_addc_u32 s13, s61, 0
	s_mov_b32 s60, m0
	s_mov_b32 m0, s79
	s_nop 0
	global_load_lds_dwordx4 v130, s[12:13]
	s_mov_b32 m0, s60
	s_nop 0
	s_mov_b32 s60, m0
	s_mov_b32 m0, s96
	s_nop 0
	global_load_lds_dwordx4 v131, s[12:13]
	s_mov_b32 m0, s60
	s_waitcnt vmcnt(8)
	s_waitcnt lgkmcnt(0)
	s_barrier
	s_waitcnt lgkmcnt(0)
	v_mfma_scale_f32_16x16x128_f8f6f4 v[124:127], v[136:143], v[168:175], v[124:127], v219, v218 op_sel_hi:[0,0,0]
	v_mfma_scale_f32_16x16x128_f8f6f4 v[120:123], v[144:151], v[168:175], v[120:123], v219, v218 op_sel_hi:[0,0,0]
	v_mfma_scale_f32_16x16x128_f8f6f4 v[112:115], v[136:143], v[176:183], v[112:115], v219, v218 op_sel_hi:[0,0,0]
	v_mfma_scale_f32_16x16x128_f8f6f4 v[104:107], v[144:151], v[176:183], v[104:107], v219, v218 op_sel_hi:[0,0,0]
	v_mfma_scale_f32_16x16x128_f8f6f4 v[96:99], v[136:143], v[184:191], v[96:99], v219, v218 op_sel_hi:[0,0,0]
	v_mfma_scale_f32_16x16x128_f8f6f4 v[194:197], v[144:151], v[184:191], v[88:91], v219, v218 op_sel_hi:[0,0,0]
	v_mfma_scale_f32_16x16x128_f8f6f4 v[206:209], v[136:143], v[198:205], v[80:83], v219, v218 op_sel_hi:[0,0,0]
	v_mfma_scale_f32_16x16x128_f8f6f4 v[210:213], v[144:151], v[198:205], v[72:75], v219, v218 op_sel_hi:[0,0,0]
	v_mfma_scale_f32_16x16x128_f8f6f4 v[116:119], v[152:159], v[168:175], v[116:119], v219, v218 op_sel_hi:[0,0,0]
	v_mfma_scale_f32_16x16x128_f8f6f4 v[108:111], v[160:167], v[168:175], v[108:111], v219, v218 op_sel_hi:[0,0,0]
	v_mfma_scale_f32_16x16x128_f8f6f4 v[100:103], v[152:159], v[176:183], v[100:103], v219, v218 op_sel_hi:[0,0,0]
	v_mfma_scale_f32_16x16x128_f8f6f4 v[168:171], v[160:167], v[176:183], v[92:95], v219, v218 op_sel_hi:[0,0,0]
	v_mfma_scale_f32_16x16x128_f8f6f4 v[172:175], v[152:159], v[184:191], v[84:87], v219, v218 op_sel_hi:[0,0,0]
	v_mfma_scale_f32_16x16x128_f8f6f4 v[176:179], v[160:167], v[184:191], v[76:79], v219, v218 op_sel_hi:[0,0,0]
	v_mfma_scale_f32_16x16x128_f8f6f4 v[180:183], v[152:159], v[198:205], v[68:71], v219, v218 op_sel_hi:[0,0,0]
	v_mfma_scale_f32_16x16x128_f8f6f4 v[184:187], v[160:167], v[198:205], v[64:67], v219, v218 op_sel_hi:[0,0,0]
	s_barrier
	s_nop 4
	ds_read_b128 v[64:67], v133 offset:16384
	ds_read_b128 v[68:71], v133 offset:17408
	ds_read_b128 v[72:75], v133 offset:18432
	ds_read_b128 v[76:79], v133 offset:19456
	ds_read_b128 v[80:83], v133 offset:20480
	ds_read_b128 v[84:87], v133 offset:21504
	ds_read_b128 v[88:91], v133 offset:22528
	ds_read_b128 v[92:95], v133 offset:23552
	s_mov_b32 s12, m0
	s_mov_b32 m0, s4
	s_nop 0
	global_load_lds_dwordx4 v130, s[56:57]
	s_mov_b32 m0, s12
	s_nop 0
	s_mov_b32 s12, m0
	s_mov_b32 m0, s5
	s_nop 0
	global_load_lds_dwordx4 v131, s[56:57]
	s_mov_b32 m0, s12
	s_add_u32 s12, s56, 0x188000
	s_addc_u32 s13, s57, 0
	s_mov_b32 s60, m0
	s_mov_b32 m0, s6
	s_nop 0
	global_load_lds_dwordx4 v130, s[12:13]
	s_mov_b32 m0, s60
	s_nop 0
	s_mov_b32 s60, m0
	s_mov_b32 m0, s7
	s_nop 0
	global_load_lds_dwordx4 v131, s[12:13]
	s_mov_b32 m0, s60
	s_mov_b32 s12, m0
	s_mov_b32 m0, s0
	s_nop 0
	global_load_lds_dwordx4 v130, s[24:25]
	s_mov_b32 m0, s12
	s_nop 0
	s_mov_b32 s12, m0
	s_mov_b32 m0, s44
	s_nop 0
	global_load_lds_dwordx4 v131, s[24:25]
	s_mov_b32 m0, s12
	s_waitcnt vmcnt(8)
	s_waitcnt lgkmcnt(0)
	s_barrier
	s_waitcnt lgkmcnt(0)
	v_mfma_scale_f32_16x16x128_f8f6f4 v[60:63], v[136:143], v[64:71], v[60:63], v219, v218 op_sel_hi:[0,0,0]
	v_mfma_scale_f32_16x16x128_f8f6f4 v[56:59], v[144:151], v[64:71], v[56:59], v219, v218 op_sel_hi:[0,0,0]
	v_mfma_scale_f32_16x16x128_f8f6f4 v[52:55], v[136:143], v[72:79], v[52:55], v219, v218 op_sel_hi:[0,0,0]
	v_mfma_scale_f32_16x16x128_f8f6f4 v[188:191], v[144:151], v[72:79], v[40:43], v219, v218 op_sel_hi:[0,0,0]
	v_mfma_scale_f32_16x16x128_f8f6f4 v[198:201], v[136:143], v[80:87], v[36:39], v219, v218 op_sel_hi:[0,0,0]
	v_mfma_scale_f32_16x16x128_f8f6f4 v[202:205], v[144:151], v[80:87], v[24:27], v219, v218 op_sel_hi:[0,0,0]
	v_mfma_scale_f32_16x16x128_f8f6f4 v[214:217], v[136:143], v[88:95], v[20:23], v219, v218 op_sel_hi:[0,0,0]
	v_mfma_scale_f32_16x16x128_f8f6f4 v[220:223], v[144:151], v[88:95], v[8:11], v219, v218 op_sel_hi:[0,0,0]
	v_mfma_scale_f32_16x16x128_f8f6f4 v[48:51], v[152:159], v[64:71], v[48:51], v219, v218 op_sel_hi:[0,0,0]
	v_mfma_scale_f32_16x16x128_f8f6f4 v[224:227], v[160:167], v[64:71], v[44:47], v219, v218 op_sel_hi:[0,0,0]
	v_mfma_scale_f32_16x16x128_f8f6f4 v[228:231], v[152:159], v[72:79], v[32:35], v219, v218 op_sel_hi:[0,0,0]
	v_mfma_scale_f32_16x16x128_f8f6f4 v[232:235], v[160:167], v[72:79], v[28:31], v219, v218 op_sel_hi:[0,0,0]
	v_mfma_scale_f32_16x16x128_f8f6f4 v[236:239], v[152:159], v[80:87], v[16:19], v219, v218 op_sel_hi:[0,0,0]
	v_mfma_scale_f32_16x16x128_f8f6f4 v[240:243], v[160:167], v[80:87], v[12:15], v219, v218 op_sel_hi:[0,0,0]
	v_mfma_scale_f32_16x16x128_f8f6f4 v[244:247], v[152:159], v[88:95], v[4:7], v219, v218 op_sel_hi:[0,0,0]
	v_mfma_scale_f32_16x16x128_f8f6f4 v[248:251], v[160:167], v[88:95], v[0:3], v219, v218 op_sel_hi:[0,0,0]
	s_barrier
	s_nop 4
	ds_read_b128 v[0:3], v134
	ds_read_b128 v[4:7], v134 offset:1024
	ds_read_b128 v[8:11], v134 offset:2048
	ds_read_b128 v[12:15], v134 offset:3072
	ds_read_b128 v[136:139], v135
	ds_read_b128 v[140:143], v135 offset:1024
	ds_read_b128 v[144:147], v135 offset:2048
	ds_read_b128 v[148:151], v135 offset:3072
	ds_read_b128 v[16:19], v133 offset:32768
	ds_read_b128 v[20:23], v133 offset:33792
	ds_read_b128 v[24:27], v133 offset:34816
	ds_read_b128 v[28:31], v133 offset:35840
	ds_read_b128 v[32:35], v133 offset:36864
	ds_read_b128 v[36:39], v133 offset:37888
	ds_read_b128 v[40:43], v133 offset:38912
	ds_read_b128 v[44:47], v133 offset:39936
	s_add_u32 s12, s24, 0x188000
	s_addc_u32 s13, s25, 0
	s_mov_b32 s24, m0
	s_mov_b32 m0, s45
	s_nop 0
	global_load_lds_dwordx4 v130, s[12:13]
	s_mov_b32 m0, s24
	s_nop 0
	s_mov_b32 s24, m0
	s_mov_b32 m0, s58
	s_nop 0
	global_load_lds_dwordx4 v131, s[12:13]
	s_mov_b32 m0, s24
	s_waitcnt vmcnt(8)
	s_waitcnt lgkmcnt(0)
	s_barrier
; #define PG8_MMA(ai, bj, At, Bt) do { __builtin_amdgcn_s_setprio(1); _Pragma("unroll") for (int m = 0; m < 4; ++m) _Pragma("unroll") for (int n = 0; n < 2; ++n) _Pragma("unroll") for (int k = 0; k < 2; ++k) \
;         acc[ai][bj][m][n] = __builtin_amdgcn_mfma_f32_16x16x32_bf16(Bt[n][k], At[m][k], acc[ai][bj][m][n], 0, 0, 0); __builtin_amdgcn_s_setprio(0); } while (0)
; #define PG8_MMA8(ai, bj, At, Bt) do { __builtin_amdgcn_s_setprio(1); _Pragma("unroll") for (int m = 0; m < 4; ++m) _Pragma("unroll") for (int n = 0; n < 2; ++n) \
;         acc[ai][bj][m][n] = __builtin_amdgcn_mfma_scale_f32_16x16x128_f8f6f4(cat8(Bt[n][0], Bt[n][1]), cat8(At[m][0], At[m][1]), acc[ai][bj][m][n], 0, 0, 0, F8_SC_W, 0, F8_SC_H); __builtin_amdgcn_s_setprio(0); } while (0)
; #define PG8_ITER_HEAD() \
;             const bool last = (t == nt - 2); \
;             const char* a1 = cA + (size_t)(t + 1) * kstep; \
;             const char* a2 = last ? nA : cA + (size_t)(t + 2) * kstep; const char* b2 = last ? nB : cB + (size_t)(t + 2) * kstep; \
;             const char* a3 = a2 + kstep; const char* b3 = b2 + kstep; \
;             if (last && has_next) S.a_ready(nxt);
;     ...
;         int t = 0;
;         if constexpr (SP2 && I8) {
;             for (; t < nt; t += 2) { PG8_ITER_HEAD() PG8_ITER_SP2(PG8_MMAI) }
;         } else if constexpr (SP2 && KS8 > 0) {
;             for (; t < KS8; t += 2) { PG8_ITER_HEAD() PG8_ITER_SP2(PG8_MMA) }
;             for (; t < nt; t += 2) { PG8_ITER_HEAD() PG8_ITER_SP2(PG8_MMA8) }
	s_waitcnt lgkmcnt(0)
	v_mfma_scale_f32_16x16x128_f8f6f4 v[124:127], v[0:7], v[16:23], v[124:127], v219, v218 op_sel_hi:[0,0,0]
	v_mfma_scale_f32_16x16x128_f8f6f4 v[120:123], v[8:15], v[16:23], v[120:123], v219, v218 op_sel_hi:[0,0,0]
	v_mfma_scale_f32_16x16x128_f8f6f4 v[112:115], v[0:7], v[24:31], v[112:115], v219, v218 op_sel_hi:[0,0,0]
	v_mfma_scale_f32_16x16x128_f8f6f4 v[104:107], v[8:15], v[24:31], v[104:107], v219, v218 op_sel_hi:[0,0,0]
	v_mfma_scale_f32_16x16x128_f8f6f4 v[96:99], v[0:7], v[32:39], v[96:99], v219, v218 op_sel_hi:[0,0,0]
	v_mfma_scale_f32_16x16x128_f8f6f4 v[88:91], v[8:15], v[32:39], v[194:197], v219, v218 op_sel_hi:[0,0,0]
	v_mfma_scale_f32_16x16x128_f8f6f4 v[80:83], v[0:7], v[40:47], v[206:209], v219, v218 op_sel_hi:[0,0,0]
	v_mfma_scale_f32_16x16x128_f8f6f4 v[72:75], v[8:15], v[40:47], v[210:213], v219, v218 op_sel_hi:[0,0,0]
	v_mfma_scale_f32_16x16x128_f8f6f4 v[116:119], v[136:143], v[16:23], v[116:119], v219, v218 op_sel_hi:[0,0,0]
	v_mfma_scale_f32_16x16x128_f8f6f4 v[108:111], v[144:151], v[16:23], v[108:111], v219, v218 op_sel_hi:[0,0,0]
	v_mfma_scale_f32_16x16x128_f8f6f4 v[100:103], v[136:143], v[24:31], v[100:103], v219, v218 op_sel_hi:[0,0,0]
	v_mfma_scale_f32_16x16x128_f8f6f4 v[92:95], v[144:151], v[24:31], v[168:171], v219, v218 op_sel_hi:[0,0,0]
	v_mfma_scale_f32_16x16x128_f8f6f4 v[84:87], v[136:143], v[32:39], v[172:175], v219, v218 op_sel_hi:[0,0,0]
	v_mfma_scale_f32_16x16x128_f8f6f4 v[76:79], v[144:151], v[32:39], v[176:179], v219, v218 op_sel_hi:[0,0,0]
	v_mfma_scale_f32_16x16x128_f8f6f4 v[68:71], v[136:143], v[40:47], v[180:183], v219, v218 op_sel_hi:[0,0,0]
	v_mfma_scale_f32_16x16x128_f8f6f4 v[64:67], v[144:151], v[40:47], v[184:187], v219, v218 op_sel_hi:[0,0,0]
	s_barrier
	ds_read_b128 v[28:31], v133 offset:49152
	ds_read_b128 v[32:35], v133 offset:50176
	ds_read_b128 v[152:155], v133 offset:51200
	ds_read_b128 v[156:159], v133 offset:52224
	ds_read_b128 v[160:163], v133 offset:53248
	ds_read_b128 v[164:167], v133 offset:54272
	ds_read_b128 v[168:171], v133 offset:55296
	ds_read_b128 v[172:175], v133 offset:56320
	s_add_u32 s12, s56, 0x80
	s_addc_u32 s13, s57, 0
	s_mov_b32 s24, m0
	s_mov_b32 m0, s73
	s_nop 0
	global_load_lds_dwordx4 v130, s[12:13]
	s_mov_b32 m0, s24
	s_nop 0
	s_mov_b32 s24, m0
	s_mov_b32 m0, s74
	s_nop 0
	global_load_lds_dwordx4 v131, s[12:13]
	s_mov_b32 m0, s24
	s_add_u32 s12, s56, 0x188080
	s_addc_u32 s13, s57, 0
	s_mov_b32 s24, m0
	s_mov_b32 m0, s77
	s_nop 0
	global_load_lds_dwordx4 v130, s[12:13]
	s_mov_b32 m0, s24
	s_nop 0
	s_mov_b32 s24, m0
	s_mov_b32 m0, s78
	s_nop 0
	global_load_lds_dwordx4 v131, s[12:13]
	s_mov_b32 m0, s24
	s_mov_b32 s12, m0
	s_mov_b32 m0, s75
	s_nop 0
	global_load_lds_dwordx4 v130, s[52:53]
	s_mov_b32 m0, s12
	s_nop 0
	s_mov_b32 s12, m0
	s_mov_b32 m0, s76
	s_nop 0
	global_load_lds_dwordx4 v131, s[52:53]
	s_mov_b32 m0, s12
	s_waitcnt vmcnt(8)
	s_waitcnt lgkmcnt(0)
	s_barrier
	s_waitcnt lgkmcnt(0)
	v_mfma_scale_f32_16x16x128_f8f6f4 v[60:63], v[0:7], v[28:35], v[60:63], v219, v218 op_sel_hi:[0,0,0]
	v_mfma_scale_f32_16x16x128_f8f6f4 v[56:59], v[8:15], v[28:35], v[56:59], v219, v218 op_sel_hi:[0,0,0]
	v_mfma_scale_f32_16x16x128_f8f6f4 v[52:55], v[0:7], v[152:159], v[52:55], v219, v218 op_sel_hi:[0,0,0]
	v_mfma_scale_f32_16x16x128_f8f6f4 v[40:43], v[8:15], v[152:159], v[188:191], v219, v218 op_sel_hi:[0,0,0]
	v_mfma_scale_f32_16x16x128_f8f6f4 v[36:39], v[0:7], v[160:167], v[198:201], v219, v218 op_sel_hi:[0,0,0]
	v_mfma_scale_f32_16x16x128_f8f6f4 v[24:27], v[8:15], v[160:167], v[202:205], v219, v218 op_sel_hi:[0,0,0]
	v_mfma_scale_f32_16x16x128_f8f6f4 v[20:23], v[0:7], v[168:175], v[214:217], v219, v218 op_sel_hi:[0,0,0]
	v_mfma_scale_f32_16x16x128_f8f6f4 v[8:11], v[8:15], v[168:175], v[220:223], v219, v218 op_sel_hi:[0,0,0]
	v_mfma_scale_f32_16x16x128_f8f6f4 v[48:51], v[136:143], v[28:35], v[48:51], v219, v218 op_sel_hi:[0,0,0]
	v_mfma_scale_f32_16x16x128_f8f6f4 v[44:47], v[144:151], v[28:35], v[224:227], v219, v218 op_sel_hi:[0,0,0]
	v_mfma_scale_f32_16x16x128_f8f6f4 v[32:35], v[136:143], v[152:159], v[228:231], v219, v218 op_sel_hi:[0,0,0]
	v_mfma_scale_f32_16x16x128_f8f6f4 v[28:31], v[144:151], v[152:159], v[232:235], v219, v218 op_sel_hi:[0,0,0]
	v_mfma_scale_f32_16x16x128_f8f6f4 v[16:19], v[136:143], v[160:167], v[236:239], v219, v218 op_sel_hi:[0,0,0]
	v_mfma_scale_f32_16x16x128_f8f6f4 v[12:15], v[144:151], v[160:167], v[240:243], v219, v218 op_sel_hi:[0,0,0]
	v_mfma_scale_f32_16x16x128_f8f6f4 v[4:7], v[136:143], v[168:175], v[244:247], v219, v218 op_sel_hi:[0,0,0]
	v_mfma_scale_f32_16x16x128_f8f6f4 v[0:3], v[144:151], v[168:175], v[248:251], v219, v218 op_sel_hi:[0,0,0]
	s_barrier
	s_add_i32 s90, s90, 2
	s_add_u32 s62, s62, 0x100
	s_addc_u32 s63, s63, 0
	s_cmpk_lt_u32 s90, 0x60
	s_mov_b64 s[60:61], s[50:51]
	s_cbranch_scc1 .LBB0_617
	v_readlane_b32 s90, v255, 19
	v_readlane_b32 s94, v255, 21
	s_andn2_b64 vcc, exec, s[42:43]
	v_readlane_b32 s91, v255, 20
	v_readlane_b32 s95, v255, 22
	s_cbranch_vccnz .LBB0_620
	s_barrier
